# redundant lgkmcnt(0) after the GEMM phase barrier removed (28 sites) + one stale s_nop in the latent-attention loop
# baseline (speedup 1.0000x reference)
; #define PG8_STAGE(bufoff, gbase, voff) do { _Pragma("unroll") for (int _i = 0; _i < 2; ++_i) \
;         __builtin_amdgcn_global_load_lds((const unsigned*)((const char*)(gbase) + (voff)[_i]), (LAS unsigned*)(lds + (bufoff) + ldsw + _i * 8192), 16, 0, 0); } while (0)
; #define PG8_LDA(dst, b, h) do { _Pragma("unroll") for (int m = 0; m < 4; ++m) _Pragma("unroll") for (int k = 0; k < 2; ++k) dst[m][k] = *(const LAS bf16x8*)(lds + PG8_SA(b, h) + aoff + m * 2048 + k * 1024); } while (0)
; #define PG8_LDB(dst, b, h) do { _Pragma("unroll") for (int n = 0; n < 2; ++n) _Pragma("unroll") for (int k = 0; k < 2; ++k) dst[n][k] = *(const LAS bf16x8*)(lds + PG8_SB(b, h) + boff + n * 2048 + k * 1024); } while (0)
; #define PG8_MMA(ai, bj, At, Bt) do { __builtin_amdgcn_s_setprio(1); _Pragma("unroll") for (int m = 0; m < 4; ++m) _Pragma("unroll") for (int n = 0; n < 2; ++n) _Pragma("unroll") for (int k = 0; k < 2; ++k) \
;         acc[ai][bj][m][n] = __builtin_amdgcn_mfma_f32_16x16x32_bf16(Bt[n][k], At[m][k], acc[ai][bj][m][n], 0, 0, 0); __builtin_amdgcn_s_setprio(0); } while (0)
; #define PG8_WAIT_V(n) asm volatile("s_waitcnt vmcnt(" #n ")" ::: "memory")
; #define PG8_WAIT_L(n) asm volatile("s_waitcnt lgkmcnt(" #n ")" ::: "memory")
; #define PG8_BAR __builtin_amdgcn_s_barrier()
; #define PG8_SCHED __builtin_amdgcn_sched_barrier(0)
; template <class EpiT, class Sched>
; __device__ __forceinline__ void gemm_phase(LAS unsigned char* lds, const Gemm g, const Sched& S, const EpiT& E, int wv) {
;     ...
;             const bool last = (t == nt - 2);
;             const char* a1 = cA + (size_t)(t + 1) * kstep;
;             const char* a2 = last ? nA : cA + (size_t)(t + 2) * kstep; const char* b2 = last ? nB : cB + (size_t)(t + 2) * kstep;
;             const char* a3 = a2 + kstep; const char* b3 = b2 + kstep;
;             PG8_LDB(B0, 0, 0); PG8_LDB(B1, 0, 1); PG8_SCHED; PG8_LDA(At, 0, 0); PG8_STAGE(PG8_SA(1, 1), a1 + hstepA, voffA);
;             PG8_WAIT_V(8); PG8_WAIT_L(0); PG8_BAR; PG8_MMA(0, 0, At, B0); PG8_MMA(0, 1, At, B1); PG8_BAR; PG8_SCHED;
;             PG8_LDA(At, 0, 1); PG8_STAGE(PG8_SB(0, 0), b2, voffB); PG8_STAGE(PG8_SB(0, 1), b2 + hstepB, voffB); PG8_STAGE(PG8_SA(0, 0), a2, voffA);
;             PG8_WAIT_V(8); PG8_WAIT_L(0); PG8_BAR; PG8_MMA(1, 0, At, B0); PG8_MMA(1, 1, At, B1); PG8_BAR; PG8_SCHED;
.LBB0_246:
	s_add_u32 s28, s26, 0xfffc0080
	s_addc_u32 s29, s27, -1
	s_add_i32 s50, 0, 0x10000
	s_cmp_eq_u32 s49, 12
	s_cselect_b32 s31, s19, s29
	s_cselect_b32 s30, s25, s28
	s_cselect_b32 s29, s17, s48
	s_cselect_b32 s28, s46, s47
	s_add_i32 s52, 0, 0x14000
	ds_read_b128 v[128:131], v250
	ds_read_b128 v[132:135], v250 offset:1024
	ds_read_b128 v[146:149], v250 offset:2048
	ds_read_b128 v[150:153], v250 offset:3072
	ds_read_b128 v[154:157], v251
	ds_read_b128 v[158:161], v251 offset:1024
	ds_read_b128 v[166:169], v251 offset:2048
	ds_read_b128 v[170:173], v251 offset:3072
	s_add_i32 m0, s36, 0xc000
	ds_read_b128 v[174:177], v165
	ds_read_b128 v[178:181], v165 offset:1024
	ds_read_b128 v[182:185], v165 offset:2048
	ds_read_b128 v[186:189], v165 offset:3072
	ds_read_b128 v[204:207], v165 offset:4096
	ds_read_b128 v[208:211], v165 offset:5120
	ds_read_b128 v[212:215], v165 offset:6144
	ds_read_b128 v[216:219], v165 offset:7168
	global_load_lds_dwordx4 v142, s[26:27]
	s_add_i32 m0, s36, 0xe000
	s_nop 0
	global_load_lds_dwordx4 v144, s[26:27]
	s_waitcnt vmcnt(8)
	s_waitcnt lgkmcnt(0)
	s_barrier
	s_setprio 1
	v_mfma_f32_16x16x32_bf16 v[124:127], v[128:131], v[174:177], v[124:127]
	v_mfma_f32_16x16x32_bf16 v[120:123], v[146:149], v[174:177], v[120:123]
	v_mfma_f32_16x16x32_bf16 v[116:119], v[128:131], v[182:185], v[116:119]
	v_mfma_f32_16x16x32_bf16 v[112:115], v[146:149], v[182:185], v[112:115]
	v_mfma_f32_16x16x32_bf16 v[108:111], v[128:131], v[204:207], v[108:111]
	v_mfma_f32_16x16x32_bf16 v[104:107], v[146:149], v[204:207], v[104:107]
	v_mfma_f32_16x16x32_bf16 v[100:103], v[128:131], v[212:215], v[100:103]
	v_mfma_f32_16x16x32_bf16 v[96:99], v[146:149], v[212:215], v[96:99]
	v_mfma_f32_16x16x32_bf16 v[124:127], v[132:135], v[178:181], v[124:127]
	v_mfma_f32_16x16x32_bf16 v[120:123], v[150:153], v[178:181], v[120:123]
	v_mfma_f32_16x16x32_bf16 v[116:119], v[132:135], v[186:189], v[116:119]
	v_mfma_f32_16x16x32_bf16 v[112:115], v[150:153], v[186:189], v[112:115]
	v_mfma_f32_16x16x32_bf16 v[108:111], v[132:135], v[208:211], v[108:111]
	v_mfma_f32_16x16x32_bf16 v[104:107], v[150:153], v[208:211], v[104:107]
	v_mfma_f32_16x16x32_bf16 v[100:103], v[132:135], v[216:219], v[100:103]
	v_mfma_f32_16x16x32_bf16 v[96:99], v[150:153], v[216:219], v[96:99]
	s_setprio 0
	s_setprio 1
	v_mfma_f32_16x16x32_bf16 v[64:67], v[154:157], v[174:177], v[64:67]
	v_mfma_f32_16x16x32_bf16 v[56:59], v[166:169], v[174:177], v[56:59]
	v_mfma_f32_16x16x32_bf16 v[52:55], v[154:157], v[182:185], v[52:55]
	v_mfma_f32_16x16x32_bf16 v[48:51], v[166:169], v[182:185], v[48:51]
	v_mfma_f32_16x16x32_bf16 v[44:47], v[154:157], v[204:207], v[44:47]
	v_mfma_f32_16x16x32_bf16 v[40:43], v[166:169], v[204:207], v[40:43]
	v_mfma_f32_16x16x32_bf16 v[36:39], v[154:157], v[212:215], v[36:39]
	v_mfma_f32_16x16x32_bf16 v[32:35], v[166:169], v[212:215], v[32:35]
	v_mfma_f32_16x16x32_bf16 v[64:67], v[158:161], v[178:181], v[64:67]
	v_mfma_f32_16x16x32_bf16 v[56:59], v[170:173], v[178:181], v[56:59]
	v_mfma_f32_16x16x32_bf16 v[52:55], v[158:161], v[186:189], v[52:55]
	v_mfma_f32_16x16x32_bf16 v[48:51], v[170:173], v[186:189], v[48:51]
	v_mfma_f32_16x16x32_bf16 v[44:47], v[158:161], v[208:211], v[44:47]
	v_mfma_f32_16x16x32_bf16 v[40:43], v[170:173], v[208:211], v[40:43]
	v_mfma_f32_16x16x32_bf16 v[36:39], v[158:161], v[216:219], v[36:39]
	v_mfma_f32_16x16x32_bf16 v[32:35], v[170:173], v[216:219], v[32:35]
	s_setprio 0
	s_barrier
	s_add_i32 s50, s50, s35
	s_add_u32 s54, s28, s92
	s_addc_u32 s55, s29, s93
	s_mov_b32 m0, s50
	ds_read_b128 v[174:177], v165 offset:16384
	ds_read_b128 v[178:181], v165 offset:17408
	ds_read_b128 v[182:185], v165 offset:18432
	ds_read_b128 v[186:189], v165 offset:19456
	ds_read_b128 v[204:207], v165 offset:20480
	ds_read_b128 v[208:211], v165 offset:21504
	ds_read_b128 v[212:215], v165 offset:22528
	ds_read_b128 v[216:219], v165 offset:23552
	global_load_lds_dwordx4 v192, s[28:29]
	s_add_i32 m0, s50, 0x2000
	s_add_u32 s50, s28, 0x40000
	s_addc_u32 s51, s29, 0
	s_add_i32 s52, s52, s35
	global_load_lds_dwordx4 v140, s[28:29]
	s_mov_b32 m0, s52
	s_nop 0
	global_load_lds_dwordx4 v192, s[50:51]
	s_add_i32 m0, s52, 0x2000
	s_nop 0
	global_load_lds_dwordx4 v140, s[50:51]
	s_add_u32 s56, s30, s92
	s_addc_u32 s57, s31, s93
	s_mov_b32 m0, s36
	s_nop 0
	global_load_lds_dwordx4 v136, s[30:31]
	s_mov_b32 m0, s37
	s_nop 0
	global_load_lds_dwordx4 v138, s[30:31]
	s_waitcnt vmcnt(8)
	s_waitcnt lgkmcnt(0)
	s_barrier
	s_setprio 1
	v_mfma_f32_16x16x32_bf16 v[92:95], v[128:131], v[174:177], v[92:95]
	v_mfma_f32_16x16x32_bf16 v[88:91], v[146:149], v[174:177], v[88:91]
	v_mfma_f32_16x16x32_bf16 v[84:87], v[128:131], v[182:185], v[84:87]
	v_mfma_f32_16x16x32_bf16 v[80:83], v[146:149], v[182:185], v[80:83]
	v_mfma_f32_16x16x32_bf16 v[76:79], v[128:131], v[204:207], v[76:79]
	v_mfma_f32_16x16x32_bf16 v[72:75], v[146:149], v[204:207], v[72:75]
	v_mfma_f32_16x16x32_bf16 v[68:71], v[128:131], v[212:215], v[68:71]
	v_mfma_f32_16x16x32_bf16 v[60:63], v[146:149], v[212:215], v[60:63]
	v_mfma_f32_16x16x32_bf16 v[92:95], v[132:135], v[178:181], v[92:95]
	v_mfma_f32_16x16x32_bf16 v[88:91], v[150:153], v[178:181], v[88:91]
	v_mfma_f32_16x16x32_bf16 v[84:87], v[132:135], v[186:189], v[84:87]
	v_mfma_f32_16x16x32_bf16 v[80:83], v[150:153], v[186:189], v[80:83]
	v_mfma_f32_16x16x32_bf16 v[76:79], v[132:135], v[208:211], v[76:79]
	v_mfma_f32_16x16x32_bf16 v[72:75], v[150:153], v[208:211], v[72:75]
	v_mfma_f32_16x16x32_bf16 v[68:71], v[132:135], v[216:219], v[68:71]
	v_mfma_f32_16x16x32_bf16 v[60:63], v[150:153], v[216:219], v[60:63]
	s_setprio 0
	s_setprio 1
	v_mfma_f32_16x16x32_bf16 v[28:31], v[154:157], v[174:177], v[28:31]
	v_mfma_f32_16x16x32_bf16 v[24:27], v[166:169], v[174:177], v[24:27]
	v_mfma_f32_16x16x32_bf16 v[20:23], v[154:157], v[182:185], v[20:23]
	v_mfma_f32_16x16x32_bf16 v[16:19], v[166:169], v[182:185], v[16:19]
	v_mfma_f32_16x16x32_bf16 v[12:15], v[154:157], v[204:207], v[12:15]
	v_mfma_f32_16x16x32_bf16 v[8:11], v[166:169], v[204:207], v[8:11]
	v_mfma_f32_16x16x32_bf16 v[4:7], v[154:157], v[212:215], v[4:7]
	v_mfma_f32_16x16x32_bf16 v[0:3], v[166:169], v[212:215], v[0:3]
	v_mfma_f32_16x16x32_bf16 v[28:31], v[158:161], v[178:181], v[28:31]
	v_mfma_f32_16x16x32_bf16 v[24:27], v[170:173], v[178:181], v[24:27]
	v_mfma_f32_16x16x32_bf16 v[20:23], v[158:161], v[186:189], v[20:23]
	v_mfma_f32_16x16x32_bf16 v[16:19], v[170:173], v[186:189], v[16:19]
	v_mfma_f32_16x16x32_bf16 v[12:15], v[158:161], v[208:211], v[12:15]
	v_mfma_f32_16x16x32_bf16 v[8:11], v[170:173], v[208:211], v[8:11]
	v_mfma_f32_16x16x32_bf16 v[4:7], v[158:161], v[216:219], v[4:7]
	v_mfma_f32_16x16x32_bf16 v[0:3], v[170:173], v[216:219], v[0:3]
	s_setprio 0
	s_barrier
; #define PG8_STAGE(bufoff, gbase, voff) do { _Pragma("unroll") for (int _i = 0; _i < 2; ++_i) \
;         __builtin_amdgcn_global_load_lds((const unsigned*)((const char*)(gbase) + (voff)[_i]), (LAS unsigned*)(lds + (bufoff) + ldsw + _i * 8192), 16, 0, 0); } while (0)
; #define PG8_LDA(dst, b, h) do { _Pragma("unroll") for (int m = 0; m < 4; ++m) _Pragma("unroll") for (int k = 0; k < 2; ++k) dst[m][k] = *(const LAS bf16x8*)(lds + PG8_SA(b, h) + aoff + m * 2048 + k * 1024); } while (0)
; #define PG8_LDB(dst, b, h) do { _Pragma("unroll") for (int n = 0; n < 2; ++n) _Pragma("unroll") for (int k = 0; k < 2; ++k) dst[n][k] = *(const LAS bf16x8*)(lds + PG8_SB(b, h) + boff + n * 2048 + k * 1024); } while (0)
; #define PG8_MMA(ai, bj, At, Bt) do { __builtin_amdgcn_s_setprio(1); _Pragma("unroll") for (int m = 0; m < 4; ++m) _Pragma("unroll") for (int n = 0; n < 2; ++n) _Pragma("unroll") for (int k = 0; k < 2; ++k) \
;         acc[ai][bj][m][n] = __builtin_amdgcn_mfma_f32_16x16x32_bf16(Bt[n][k], At[m][k], acc[ai][bj][m][n], 0, 0, 0); __builtin_amdgcn_s_setprio(0); } while (0)
; #define PG8_WAIT_V(n) asm volatile("s_waitcnt vmcnt(" #n ")" ::: "memory")
; #define PG8_WAIT_L(n) asm volatile("s_waitcnt lgkmcnt(" #n ")" ::: "memory")
; #define PG8_BAR __builtin_amdgcn_s_barrier()
; #define PG8_SCHED __builtin_amdgcn_sched_barrier(0)
; template <class EpiT, class Sched>
; __device__ __forceinline__ void gemm_phase(LAS unsigned char* lds, const Gemm g, const Sched& S, const EpiT& E, int wv) {
;     ...
;             PG8_LDB(B0, 1, 0); PG8_LDB(B1, 1, 1); PG8_SCHED; PG8_LDA(At, 1, 0); PG8_STAGE(PG8_SA(0, 1), a2 + hstepA, voffA);
;             PG8_WAIT_V(8); PG8_WAIT_L(0); PG8_BAR; PG8_MMA(0, 0, At, B0); PG8_MMA(0, 1, At, B1); PG8_BAR; PG8_SCHED;
;             PG8_LDA(At, 1, 1); PG8_STAGE(PG8_SB(1, 0), b3, voffB); PG8_STAGE(PG8_SB(1, 1), b3 + hstepB, voffB); PG8_STAGE(PG8_SA(1, 0), a3, voffA);
;             PG8_WAIT_V(8); PG8_WAIT_L(0); PG8_BAR; PG8_MMA(1, 0, At, B0); PG8_MMA(1, 1, At, B1); PG8_BAR; PG8_SCHED;
;         }
;         if (wr == 0) PG8_BAR;
	s_add_i32 s50, 0, 0x18000
	s_add_i32 s51, 0, 0x1c000
	ds_read_b128 v[128:131], v252
	ds_read_b128 v[132:135], v252 offset:1024
	ds_read_b128 v[146:149], v252 offset:2048
	ds_read_b128 v[150:153], v252 offset:3072
	ds_read_b128 v[154:157], v253
	ds_read_b128 v[158:161], v253 offset:1024
	ds_read_b128 v[166:169], v253 offset:2048
	ds_read_b128 v[170:173], v253 offset:3072
	s_add_u32 s30, s30, 0x40000
	s_addc_u32 s31, s31, 0
	s_mov_b32 m0, s38
	ds_read_b128 v[174:177], v165 offset:32768
	ds_read_b128 v[178:181], v165 offset:33792
	ds_read_b128 v[182:185], v165 offset:34816
	ds_read_b128 v[186:189], v165 offset:35840
	ds_read_b128 v[204:207], v165 offset:36864
	ds_read_b128 v[208:211], v165 offset:37888
	ds_read_b128 v[212:215], v165 offset:38912
	ds_read_b128 v[216:219], v165 offset:39936
	global_load_lds_dwordx4 v136, s[30:31]
	s_mov_b32 m0, s39
	s_nop 0
	global_load_lds_dwordx4 v138, s[30:31]
	s_waitcnt vmcnt(8)
	s_waitcnt lgkmcnt(0)
	s_barrier
	s_setprio 1
	v_mfma_f32_16x16x32_bf16 v[124:127], v[128:131], v[174:177], v[124:127]
	v_mfma_f32_16x16x32_bf16 v[120:123], v[146:149], v[174:177], v[120:123]
	v_mfma_f32_16x16x32_bf16 v[116:119], v[128:131], v[182:185], v[116:119]
	v_mfma_f32_16x16x32_bf16 v[112:115], v[146:149], v[182:185], v[112:115]
	v_mfma_f32_16x16x32_bf16 v[108:111], v[128:131], v[204:207], v[108:111]
	v_mfma_f32_16x16x32_bf16 v[104:107], v[146:149], v[204:207], v[104:107]
	v_mfma_f32_16x16x32_bf16 v[100:103], v[128:131], v[212:215], v[100:103]
	v_mfma_f32_16x16x32_bf16 v[96:99], v[146:149], v[212:215], v[96:99]
	v_mfma_f32_16x16x32_bf16 v[124:127], v[132:135], v[178:181], v[124:127]
	v_mfma_f32_16x16x32_bf16 v[120:123], v[150:153], v[178:181], v[120:123]
	v_mfma_f32_16x16x32_bf16 v[116:119], v[132:135], v[186:189], v[116:119]
	v_mfma_f32_16x16x32_bf16 v[112:115], v[150:153], v[186:189], v[112:115]
	v_mfma_f32_16x16x32_bf16 v[108:111], v[132:135], v[208:211], v[108:111]
	v_mfma_f32_16x16x32_bf16 v[104:107], v[150:153], v[208:211], v[104:107]
	v_mfma_f32_16x16x32_bf16 v[100:103], v[132:135], v[216:219], v[100:103]
	v_mfma_f32_16x16x32_bf16 v[96:99], v[150:153], v[216:219], v[96:99]
	s_setprio 0
	s_setprio 1
	v_mfma_f32_16x16x32_bf16 v[64:67], v[154:157], v[174:177], v[64:67]
	v_mfma_f32_16x16x32_bf16 v[56:59], v[166:169], v[174:177], v[56:59]
	v_mfma_f32_16x16x32_bf16 v[52:55], v[154:157], v[182:185], v[52:55]
	v_mfma_f32_16x16x32_bf16 v[48:51], v[166:169], v[182:185], v[48:51]
	v_mfma_f32_16x16x32_bf16 v[44:47], v[154:157], v[204:207], v[44:47]
	v_mfma_f32_16x16x32_bf16 v[40:43], v[166:169], v[204:207], v[40:43]
	v_mfma_f32_16x16x32_bf16 v[36:39], v[154:157], v[212:215], v[36:39]
	v_mfma_f32_16x16x32_bf16 v[32:35], v[166:169], v[212:215], v[32:35]
	v_mfma_f32_16x16x32_bf16 v[64:67], v[158:161], v[178:181], v[64:67]
	v_mfma_f32_16x16x32_bf16 v[56:59], v[170:173], v[178:181], v[56:59]
	v_mfma_f32_16x16x32_bf16 v[52:55], v[158:161], v[186:189], v[52:55]
	v_mfma_f32_16x16x32_bf16 v[48:51], v[170:173], v[186:189], v[48:51]
	v_mfma_f32_16x16x32_bf16 v[44:47], v[158:161], v[208:211], v[44:47]
	v_mfma_f32_16x16x32_bf16 v[40:43], v[170:173], v[208:211], v[40:43]
	v_mfma_f32_16x16x32_bf16 v[36:39], v[158:161], v[216:219], v[36:39]
	v_mfma_f32_16x16x32_bf16 v[32:35], v[170:173], v[216:219], v[32:35]
	s_setprio 0
	s_barrier
	s_add_i32 s30, s50, s35
	s_mov_b32 m0, s30
	ds_read_b128 v[174:177], v165 offset:49152
	ds_read_b128 v[178:181], v165 offset:50176
	ds_read_b128 v[182:185], v165 offset:51200
	ds_read_b128 v[186:189], v165 offset:52224
	ds_read_b128 v[204:207], v165 offset:53248
	ds_read_b128 v[208:211], v165 offset:54272
	ds_read_b128 v[212:215], v165 offset:55296
	ds_read_b128 v[216:219], v165 offset:56320
	global_load_lds_dwordx4 v192, s[54:55]
	s_add_i32 m0, s30, 0x2000
	s_add_u32 s28, s28, 0x40080
	s_addc_u32 s29, s29, 0
	s_add_i32 s30, s51, s35
	global_load_lds_dwordx4 v140, s[54:55]
	s_mov_b32 m0, s30
	s_nop 0
	global_load_lds_dwordx4 v192, s[28:29]
	s_add_i32 m0, s30, 0x2000
	s_nop 0
	global_load_lds_dwordx4 v140, s[28:29]
	s_mov_b32 m0, s40
	s_nop 0
	global_load_lds_dwordx4 v136, s[56:57]
	s_mov_b32 m0, s41
	s_nop 0
	global_load_lds_dwordx4 v138, s[56:57]
	s_waitcnt vmcnt(8)
	s_waitcnt lgkmcnt(0)
	s_barrier
	s_setprio 1
	v_mfma_f32_16x16x32_bf16 v[92:95], v[128:131], v[174:177], v[92:95]
	v_mfma_f32_16x16x32_bf16 v[88:91], v[146:149], v[174:177], v[88:91]
	v_mfma_f32_16x16x32_bf16 v[84:87], v[128:131], v[182:185], v[84:87]
	v_mfma_f32_16x16x32_bf16 v[80:83], v[146:149], v[182:185], v[80:83]
	v_mfma_f32_16x16x32_bf16 v[76:79], v[128:131], v[204:207], v[76:79]
	v_mfma_f32_16x16x32_bf16 v[72:75], v[146:149], v[204:207], v[72:75]
	v_mfma_f32_16x16x32_bf16 v[68:71], v[128:131], v[212:215], v[68:71]
	v_mfma_f32_16x16x32_bf16 v[60:63], v[146:149], v[212:215], v[60:63]
	v_mfma_f32_16x16x32_bf16 v[92:95], v[132:135], v[178:181], v[92:95]
	v_mfma_f32_16x16x32_bf16 v[88:91], v[150:153], v[178:181], v[88:91]
	v_mfma_f32_16x16x32_bf16 v[84:87], v[132:135], v[186:189], v[84:87]
	v_mfma_f32_16x16x32_bf16 v[80:83], v[150:153], v[186:189], v[80:83]
	v_mfma_f32_16x16x32_bf16 v[76:79], v[132:135], v[208:211], v[76:79]
	v_mfma_f32_16x16x32_bf16 v[72:75], v[150:153], v[208:211], v[72:75]
	v_mfma_f32_16x16x32_bf16 v[68:71], v[132:135], v[216:219], v[68:71]
	v_mfma_f32_16x16x32_bf16 v[60:63], v[150:153], v[216:219], v[60:63]
	s_setprio 0
	s_setprio 1
	v_mfma_f32_16x16x32_bf16 v[28:31], v[154:157], v[174:177], v[28:31]
	v_mfma_f32_16x16x32_bf16 v[24:27], v[166:169], v[174:177], v[24:27]
	v_mfma_f32_16x16x32_bf16 v[20:23], v[154:157], v[182:185], v[20:23]
	v_mfma_f32_16x16x32_bf16 v[16:19], v[166:169], v[182:185], v[16:19]
	v_mfma_f32_16x16x32_bf16 v[12:15], v[154:157], v[204:207], v[12:15]
	v_mfma_f32_16x16x32_bf16 v[8:11], v[166:169], v[204:207], v[8:11]
	v_mfma_f32_16x16x32_bf16 v[4:7], v[154:157], v[212:215], v[4:7]
	v_mfma_f32_16x16x32_bf16 v[0:3], v[166:169], v[212:215], v[0:3]
	v_mfma_f32_16x16x32_bf16 v[28:31], v[158:161], v[178:181], v[28:31]
	v_mfma_f32_16x16x32_bf16 v[24:27], v[170:173], v[178:181], v[24:27]
	v_mfma_f32_16x16x32_bf16 v[20:23], v[158:161], v[186:189], v[20:23]
	v_mfma_f32_16x16x32_bf16 v[16:19], v[170:173], v[186:189], v[16:19]
	v_mfma_f32_16x16x32_bf16 v[12:15], v[158:161], v[208:211], v[12:15]
	v_mfma_f32_16x16x32_bf16 v[8:11], v[170:173], v[208:211], v[8:11]
	v_mfma_f32_16x16x32_bf16 v[4:7], v[158:161], v[216:219], v[4:7]
	v_mfma_f32_16x16x32_bf16 v[0:3], v[170:173], v[216:219], v[0:3]
	s_setprio 0
	s_barrier
	s_add_i32 s49, s49, 2
	s_add_u32 s26, s26, 0x100
	s_addc_u32 s27, s27, 0
	s_add_u32 s47, s47, 0x100
	s_addc_u32 s48, s48, 0
	s_cmp_gt_u32 s49, 13
	s_cbranch_scc0 .LBB0_246
	s_and_b64 vcc, exec, s[12:13]
	s_cbranch_vccz .LBB0_249
	s_barrier

; #define PG8_STAGE(bufoff, gbase, voff) do { _Pragma("unroll") for (int _i = 0; _i < 2; ++_i) \
;         __builtin_amdgcn_global_load_lds((const unsigned*)((const char*)(gbase) + (voff)[_i]), (LAS unsigned*)(lds + (bufoff) + ldsw + _i * 8192), 16, 0, 0); } while (0)
; #define PG8_LDA(dst, b, h) do { _Pragma("unroll") for (int m = 0; m < 4; ++m) _Pragma("unroll") for (int k = 0; k < 2; ++k) dst[m][k] = *(const LAS bf16x8*)(lds + PG8_SA(b, h) + aoff + m * 2048 + k * 1024); } while (0)
; #define PG8_LDB(dst, b, h) do { _Pragma("unroll") for (int n = 0; n < 2; ++n) _Pragma("unroll") for (int k = 0; k < 2; ++k) dst[n][k] = *(const LAS bf16x8*)(lds + PG8_SB(b, h) + boff + n * 2048 + k * 1024); } while (0)
; #define PG8_MMA(ai, bj, At, Bt) do { __builtin_amdgcn_s_setprio(1); _Pragma("unroll") for (int m = 0; m < 4; ++m) _Pragma("unroll") for (int n = 0; n < 2; ++n) _Pragma("unroll") for (int k = 0; k < 2; ++k) \
;         acc[ai][bj][m][n] = __builtin_amdgcn_mfma_f32_16x16x32_bf16(Bt[n][k], At[m][k], acc[ai][bj][m][n], 0, 0, 0); __builtin_amdgcn_s_setprio(0); } while (0)
; #define PG8_WAIT_V(n) asm volatile("s_waitcnt vmcnt(" #n ")" ::: "memory")
; #define PG8_WAIT_L(n) asm volatile("s_waitcnt lgkmcnt(" #n ")" ::: "memory")
; #define PG8_BAR __builtin_amdgcn_s_barrier()
; #define PG8_SCHED __builtin_amdgcn_sched_barrier(0)
; template <class EpiT, class Sched>
; __device__ __forceinline__ void gemm_phase(LAS unsigned char* lds, const Gemm g, const Sched& S, const EpiT& E, int wv) {
;     ...
;             const bool last = (t == nt - 2);
;             const char* a1 = cA + (size_t)(t + 1) * kstep;
;             const char* a2 = last ? nA : cA + (size_t)(t + 2) * kstep; const char* b2 = last ? nB : cB + (size_t)(t + 2) * kstep;
;             const char* a3 = a2 + kstep; const char* b3 = b2 + kstep;
;             PG8_LDB(B0, 0, 0); PG8_LDB(B1, 0, 1); PG8_SCHED; PG8_LDA(At, 0, 0); PG8_STAGE(PG8_SA(1, 1), a1 + hstepA, voffA);
;             PG8_WAIT_V(8); PG8_WAIT_L(0); PG8_BAR; PG8_MMA(0, 0, At, B0); PG8_MMA(0, 1, At, B1); PG8_BAR; PG8_SCHED;
;             PG8_LDA(At, 0, 1); PG8_STAGE(PG8_SB(0, 0), b2, voffB); PG8_STAGE(PG8_SB(0, 1), b2 + hstepB, voffB); PG8_STAGE(PG8_SA(0, 0), a2, voffA);
;             PG8_WAIT_V(8); PG8_WAIT_L(0); PG8_BAR; PG8_MMA(1, 0, At, B0); PG8_MMA(1, 1, At, B1); PG8_BAR; PG8_SCHED;
.LBB0_472:
	s_add_i32 s9, s4, 2
	s_add_u32 s11, s0, 0x80
	s_addc_u32 s5, s1, 0
	s_add_i32 s33, 0, 0x10000
	s_cmp_eq_u32 s58, s4
	s_cselect_b32 s5, s35, s5
	s_cselect_b32 s4, s34, s11
	s_cselect_b32 s39, s37, s7
	s_cselect_b32 s38, s36, s6
	s_add_i32 s11, 0, 0x14000
	ds_read_b128 v[128:131], v250
	ds_read_b128 v[142:145], v250 offset:1024
	ds_read_b128 v[146:149], v250 offset:2048
	ds_read_b128 v[150:153], v250 offset:3072
	ds_read_b128 v[154:157], v251
	ds_read_b128 v[160:163], v251 offset:1024
	ds_read_b128 v[164:167], v251 offset:2048
	ds_read_b128 v[168:171], v251 offset:3072
	v_lshl_add_u64 v[216:217], s[0:1], 0, v[138:139]
	s_add_i32 m0, s50, 0xc000
	ds_read_b128 v[172:175], v159
	ds_read_b128 v[176:179], v159 offset:1024
	ds_read_b128 v[180:183], v159 offset:2048
	ds_read_b128 v[184:187], v159 offset:3072
	ds_read_b128 v[188:191], v159 offset:4096
	ds_read_b128 v[204:207], v159 offset:5120
	ds_read_b128 v[208:211], v159 offset:6144
	ds_read_b128 v[212:215], v159 offset:7168
	global_load_lds_dwordx4 v[216:217], off
	v_lshl_add_u64 v[216:217], s[0:1], 0, v[140:141]
	s_add_i32 m0, s50, 0xe000
	s_nop 0
	global_load_lds_dwordx4 v[216:217], off
	s_waitcnt vmcnt(8)
	s_waitcnt lgkmcnt(0)
	s_barrier
	s_setprio 1
	v_mfma_f32_16x16x32_bf16 v[120:123], v[128:131], v[172:175], v[120:123]
	v_mfma_f32_16x16x32_bf16 v[124:127], v[146:149], v[172:175], v[124:127]
	v_mfma_f32_16x16x32_bf16 v[116:119], v[128:131], v[180:183], v[116:119]
	v_mfma_f32_16x16x32_bf16 v[112:115], v[146:149], v[180:183], v[112:115]
	v_mfma_f32_16x16x32_bf16 v[108:111], v[128:131], v[188:191], v[108:111]
	v_mfma_f32_16x16x32_bf16 v[104:107], v[146:149], v[188:191], v[104:107]
	v_mfma_f32_16x16x32_bf16 v[100:103], v[128:131], v[208:211], v[100:103]
	v_mfma_f32_16x16x32_bf16 v[96:99], v[146:149], v[208:211], v[96:99]
	v_mfma_f32_16x16x32_bf16 v[120:123], v[142:145], v[176:179], v[120:123]
	v_mfma_f32_16x16x32_bf16 v[124:127], v[150:153], v[176:179], v[124:127]
	v_mfma_f32_16x16x32_bf16 v[116:119], v[142:145], v[184:187], v[116:119]
	v_mfma_f32_16x16x32_bf16 v[112:115], v[150:153], v[184:187], v[112:115]
	v_mfma_f32_16x16x32_bf16 v[108:111], v[142:145], v[204:207], v[108:111]
	v_mfma_f32_16x16x32_bf16 v[104:107], v[150:153], v[204:207], v[104:107]
	v_mfma_f32_16x16x32_bf16 v[100:103], v[142:145], v[212:215], v[100:103]
	v_mfma_f32_16x16x32_bf16 v[96:99], v[150:153], v[212:215], v[96:99]
	s_setprio 0
	s_setprio 1
	v_mfma_f32_16x16x32_bf16 v[60:63], v[154:157], v[172:175], v[60:63]
	v_mfma_f32_16x16x32_bf16 v[56:59], v[164:167], v[172:175], v[56:59]
	v_mfma_f32_16x16x32_bf16 v[52:55], v[154:157], v[180:183], v[52:55]
	v_mfma_f32_16x16x32_bf16 v[48:51], v[164:167], v[180:183], v[48:51]
	v_mfma_f32_16x16x32_bf16 v[44:47], v[154:157], v[188:191], v[44:47]
	v_mfma_f32_16x16x32_bf16 v[40:43], v[164:167], v[188:191], v[40:43]
	v_mfma_f32_16x16x32_bf16 v[36:39], v[154:157], v[208:211], v[36:39]
	v_mfma_f32_16x16x32_bf16 v[32:35], v[164:167], v[208:211], v[32:35]
	v_mfma_f32_16x16x32_bf16 v[60:63], v[160:163], v[176:179], v[60:63]
	v_mfma_f32_16x16x32_bf16 v[56:59], v[168:171], v[176:179], v[56:59]
	v_mfma_f32_16x16x32_bf16 v[52:55], v[160:163], v[184:187], v[52:55]
	v_mfma_f32_16x16x32_bf16 v[48:51], v[168:171], v[184:187], v[48:51]
	v_mfma_f32_16x16x32_bf16 v[44:47], v[160:163], v[204:207], v[44:47]
	v_mfma_f32_16x16x32_bf16 v[40:43], v[168:171], v[204:207], v[40:43]
	v_mfma_f32_16x16x32_bf16 v[36:39], v[160:163], v[212:215], v[36:39]
	v_mfma_f32_16x16x32_bf16 v[32:35], v[168:171], v[212:215], v[32:35]
	s_setprio 0
	s_barrier
	s_add_i32 s33, s33, s49
	v_lshl_add_u64 v[216:217], s[38:39], 0, v[192:193]
	s_mov_b32 m0, s33
	ds_read_b128 v[172:175], v159 offset:16384
	ds_read_b128 v[176:179], v159 offset:17408
	ds_read_b128 v[180:183], v159 offset:18432
	ds_read_b128 v[184:187], v159 offset:19456
	ds_read_b128 v[188:191], v159 offset:20480
	ds_read_b128 v[204:207], v159 offset:21504
	ds_read_b128 v[208:211], v159 offset:22528
	ds_read_b128 v[212:215], v159 offset:23552
	global_load_lds_dwordx4 v[216:217], off
	s_add_i32 m0, s33, 0x2000
	v_lshl_add_u64 v[218:219], s[38:39], 0, v[136:137]
	s_add_u32 s38, s38, s16
	s_addc_u32 s39, s39, s17
	s_add_i32 s11, s11, s49
	global_load_lds_dwordx4 v[218:219], off
	v_lshl_add_u64 v[220:221], s[38:39], 0, v[192:193]
	s_mov_b32 m0, s11
	v_lshl_add_u64 v[222:223], s[38:39], 0, v[136:137]
	global_load_lds_dwordx4 v[220:221], off
	s_add_i32 m0, s11, 0x2000
	v_lshl_add_u64 v[232:233], s[4:5], 0, v[132:133]
	global_load_lds_dwordx4 v[222:223], off
	s_mov_b32 m0, s50
	v_lshl_add_u64 v[234:235], s[4:5], 0, v[134:135]
	global_load_lds_dwordx4 v[232:233], off
	s_mov_b32 m0, s51
	s_nop 0
	global_load_lds_dwordx4 v[234:235], off
	s_waitcnt vmcnt(8)
	s_waitcnt lgkmcnt(0)
	s_barrier
; #define PG8_STAGE(bufoff, gbase, voff) do { _Pragma("unroll") for (int _i = 0; _i < 2; ++_i) \
;         __builtin_amdgcn_global_load_lds((const unsigned*)((const char*)(gbase) + (voff)[_i]), (LAS unsigned*)(lds + (bufoff) + ldsw + _i * 8192), 16, 0, 0); } while (0)
; #define PG8_LDA(dst, b, h) do { _Pragma("unroll") for (int m = 0; m < 4; ++m) _Pragma("unroll") for (int k = 0; k < 2; ++k) dst[m][k] = *(const LAS bf16x8*)(lds + PG8_SA(b, h) + aoff + m * 2048 + k * 1024); } while (0)
; #define PG8_LDB(dst, b, h) do { _Pragma("unroll") for (int n = 0; n < 2; ++n) _Pragma("unroll") for (int k = 0; k < 2; ++k) dst[n][k] = *(const LAS bf16x8*)(lds + PG8_SB(b, h) + boff + n * 2048 + k * 1024); } while (0)
; #define PG8_MMA(ai, bj, At, Bt) do { __builtin_amdgcn_s_setprio(1); _Pragma("unroll") for (int m = 0; m < 4; ++m) _Pragma("unroll") for (int n = 0; n < 2; ++n) _Pragma("unroll") for (int k = 0; k < 2; ++k) \
;         acc[ai][bj][m][n] = __builtin_amdgcn_mfma_f32_16x16x32_bf16(Bt[n][k], At[m][k], acc[ai][bj][m][n], 0, 0, 0); __builtin_amdgcn_s_setprio(0); } while (0)
; #define PG8_WAIT_V(n) asm volatile("s_waitcnt vmcnt(" #n ")" ::: "memory")
; #define PG8_WAIT_L(n) asm volatile("s_waitcnt lgkmcnt(" #n ")" ::: "memory")
; #define PG8_BAR __builtin_amdgcn_s_barrier()
; #define PG8_SCHED __builtin_amdgcn_sched_barrier(0)
; template <class EpiT, class Sched>
; __device__ __forceinline__ void gemm_phase(LAS unsigned char* lds, const Gemm g, const Sched& S, const EpiT& E, int wv) {
;     ...
;             PG8_WAIT_V(8); PG8_WAIT_L(0); PG8_BAR; PG8_MMA(1, 0, At, B0); PG8_MMA(1, 1, At, B1); PG8_BAR; PG8_SCHED;
;             PG8_LDB(B0, 1, 0); PG8_LDB(B1, 1, 1); PG8_SCHED; PG8_LDA(At, 1, 0); PG8_STAGE(PG8_SA(0, 1), a2 + hstepA, voffA);
;             PG8_WAIT_V(8); PG8_WAIT_L(0); PG8_BAR; PG8_MMA(0, 0, At, B0); PG8_MMA(0, 1, At, B1); PG8_BAR; PG8_SCHED;
	s_setprio 1
	v_mfma_f32_16x16x32_bf16 v[92:95], v[128:131], v[172:175], v[92:95]
	v_mfma_f32_16x16x32_bf16 v[88:91], v[146:149], v[172:175], v[88:91]
	v_mfma_f32_16x16x32_bf16 v[84:87], v[128:131], v[180:183], v[84:87]
	v_mfma_f32_16x16x32_bf16 v[80:83], v[146:149], v[180:183], v[80:83]
	v_mfma_f32_16x16x32_bf16 v[76:79], v[128:131], v[188:191], v[76:79]
	v_mfma_f32_16x16x32_bf16 v[72:75], v[146:149], v[188:191], v[72:75]
	v_mfma_f32_16x16x32_bf16 v[68:71], v[128:131], v[208:211], v[68:71]
	v_mfma_f32_16x16x32_bf16 v[64:67], v[146:149], v[208:211], v[64:67]
	v_mfma_f32_16x16x32_bf16 v[92:95], v[142:145], v[176:179], v[92:95]
	v_mfma_f32_16x16x32_bf16 v[88:91], v[150:153], v[176:179], v[88:91]
	v_mfma_f32_16x16x32_bf16 v[84:87], v[142:145], v[184:187], v[84:87]
	v_mfma_f32_16x16x32_bf16 v[80:83], v[150:153], v[184:187], v[80:83]
	v_mfma_f32_16x16x32_bf16 v[76:79], v[142:145], v[204:207], v[76:79]
	v_mfma_f32_16x16x32_bf16 v[72:75], v[150:153], v[204:207], v[72:75]
	v_mfma_f32_16x16x32_bf16 v[68:71], v[142:145], v[212:215], v[68:71]
	v_mfma_f32_16x16x32_bf16 v[64:67], v[150:153], v[212:215], v[64:67]
	s_setprio 0
	s_setprio 1
	v_mfma_f32_16x16x32_bf16 v[28:31], v[154:157], v[172:175], v[28:31]
	v_mfma_f32_16x16x32_bf16 v[24:27], v[164:167], v[172:175], v[24:27]
	v_mfma_f32_16x16x32_bf16 v[20:23], v[154:157], v[180:183], v[20:23]
	v_mfma_f32_16x16x32_bf16 v[16:19], v[164:167], v[180:183], v[16:19]
	v_mfma_f32_16x16x32_bf16 v[12:15], v[154:157], v[188:191], v[12:15]
	v_mfma_f32_16x16x32_bf16 v[8:11], v[164:167], v[188:191], v[8:11]
	v_mfma_f32_16x16x32_bf16 v[4:7], v[154:157], v[208:211], v[4:7]
	v_mfma_f32_16x16x32_bf16 v[0:3], v[164:167], v[208:211], v[0:3]
	v_mfma_f32_16x16x32_bf16 v[28:31], v[160:163], v[176:179], v[28:31]
	v_mfma_f32_16x16x32_bf16 v[24:27], v[168:171], v[176:179], v[24:27]
	v_mfma_f32_16x16x32_bf16 v[20:23], v[160:163], v[184:187], v[20:23]
	v_mfma_f32_16x16x32_bf16 v[16:19], v[168:171], v[184:187], v[16:19]
	v_mfma_f32_16x16x32_bf16 v[12:15], v[160:163], v[204:207], v[12:15]
	v_mfma_f32_16x16x32_bf16 v[8:11], v[168:171], v[204:207], v[8:11]
	v_mfma_f32_16x16x32_bf16 v[4:7], v[160:163], v[212:215], v[4:7]
	v_mfma_f32_16x16x32_bf16 v[0:3], v[168:171], v[212:215], v[0:3]
	s_setprio 0
	s_barrier
	s_add_i32 s11, 0, 0x18000
	s_add_i32 s33, 0, 0x1c000
	ds_read_b128 v[128:131], v252
	ds_read_b128 v[142:145], v252 offset:1024
	ds_read_b128 v[146:149], v252 offset:2048
	ds_read_b128 v[150:153], v252 offset:3072
	ds_read_b128 v[154:157], v253
	ds_read_b128 v[160:163], v253 offset:1024
	ds_read_b128 v[164:167], v253 offset:2048
	ds_read_b128 v[168:171], v253 offset:3072
	s_add_u32 s4, s4, s16
	s_addc_u32 s5, s5, s17
	s_mov_b32 m0, s52
	v_lshl_add_u64 v[240:241], s[4:5], 0, v[132:133]
	ds_read_b128 v[172:175], v159 offset:32768
	ds_read_b128 v[176:179], v159 offset:33792
	ds_read_b128 v[180:183], v159 offset:34816
	ds_read_b128 v[184:187], v159 offset:35840
	ds_read_b128 v[188:191], v159 offset:36864
	ds_read_b128 v[204:207], v159 offset:37888
	ds_read_b128 v[208:211], v159 offset:38912
	ds_read_b128 v[212:215], v159 offset:39936
	global_load_lds_dwordx4 v[240:241], off
	v_lshl_add_u64 v[240:241], s[4:5], 0, v[134:135]
	s_mov_b32 m0, s53
	s_nop 0
	global_load_lds_dwordx4 v[240:241], off
	s_waitcnt vmcnt(8)
	s_waitcnt lgkmcnt(0)
	s_barrier
	s_setprio 1
	v_mfma_f32_16x16x32_bf16 v[120:123], v[128:131], v[172:175], v[120:123]
	v_mfma_f32_16x16x32_bf16 v[124:127], v[146:149], v[172:175], v[124:127]
	v_mfma_f32_16x16x32_bf16 v[116:119], v[128:131], v[180:183], v[116:119]
	v_mfma_f32_16x16x32_bf16 v[112:115], v[146:149], v[180:183], v[112:115]
	v_mfma_f32_16x16x32_bf16 v[108:111], v[128:131], v[188:191], v[108:111]
	v_mfma_f32_16x16x32_bf16 v[104:107], v[146:149], v[188:191], v[104:107]
	v_mfma_f32_16x16x32_bf16 v[100:103], v[128:131], v[208:211], v[100:103]
	v_mfma_f32_16x16x32_bf16 v[96:99], v[146:149], v[208:211], v[96:99]
	v_mfma_f32_16x16x32_bf16 v[120:123], v[142:145], v[176:179], v[120:123]
	v_mfma_f32_16x16x32_bf16 v[124:127], v[150:153], v[176:179], v[124:127]
	v_mfma_f32_16x16x32_bf16 v[116:119], v[142:145], v[184:187], v[116:119]
	v_mfma_f32_16x16x32_bf16 v[112:115], v[150:153], v[184:187], v[112:115]
	v_mfma_f32_16x16x32_bf16 v[108:111], v[142:145], v[204:207], v[108:111]
	v_mfma_f32_16x16x32_bf16 v[104:107], v[150:153], v[204:207], v[104:107]
	v_mfma_f32_16x16x32_bf16 v[100:103], v[142:145], v[212:215], v[100:103]
	v_mfma_f32_16x16x32_bf16 v[96:99], v[150:153], v[212:215], v[96:99]
	s_setprio 0
	s_setprio 1
	v_mfma_f32_16x16x32_bf16 v[60:63], v[154:157], v[172:175], v[60:63]
	v_mfma_f32_16x16x32_bf16 v[56:59], v[164:167], v[172:175], v[56:59]
	v_mfma_f32_16x16x32_bf16 v[52:55], v[154:157], v[180:183], v[52:55]
	v_mfma_f32_16x16x32_bf16 v[48:51], v[164:167], v[180:183], v[48:51]
	v_mfma_f32_16x16x32_bf16 v[44:47], v[154:157], v[188:191], v[44:47]
	v_mfma_f32_16x16x32_bf16 v[40:43], v[164:167], v[188:191], v[40:43]
	v_mfma_f32_16x16x32_bf16 v[36:39], v[154:157], v[208:211], v[36:39]
	v_mfma_f32_16x16x32_bf16 v[32:35], v[164:167], v[208:211], v[32:35]
	v_mfma_f32_16x16x32_bf16 v[60:63], v[160:163], v[176:179], v[60:63]
	v_mfma_f32_16x16x32_bf16 v[56:59], v[168:171], v[176:179], v[56:59]
	v_mfma_f32_16x16x32_bf16 v[52:55], v[160:163], v[184:187], v[52:55]
	v_mfma_f32_16x16x32_bf16 v[48:51], v[168:171], v[184:187], v[48:51]
	v_mfma_f32_16x16x32_bf16 v[44:47], v[160:163], v[204:207], v[44:47]
	v_mfma_f32_16x16x32_bf16 v[40:43], v[168:171], v[204:207], v[40:43]
	v_mfma_f32_16x16x32_bf16 v[36:39], v[160:163], v[212:215], v[36:39]
	v_mfma_f32_16x16x32_bf16 v[32:35], v[168:171], v[212:215], v[32:35]
	s_setprio 0
	s_barrier
; #define PG8_STAGE(bufoff, gbase, voff) do { _Pragma("unroll") for (int _i = 0; _i < 2; ++_i) \
;         __builtin_amdgcn_global_load_lds((const unsigned*)((const char*)(gbase) + (voff)[_i]), (LAS unsigned*)(lds + (bufoff) + ldsw + _i * 8192), 16, 0, 0); } while (0)
; #define PG8_LDA(dst, b, h) do { _Pragma("unroll") for (int m = 0; m < 4; ++m) _Pragma("unroll") for (int k = 0; k < 2; ++k) dst[m][k] = *(const LAS bf16x8*)(lds + PG8_SA(b, h) + aoff + m * 2048 + k * 1024); } while (0)
; #define PG8_MMA(ai, bj, At, Bt) do { __builtin_amdgcn_s_setprio(1); _Pragma("unroll") for (int m = 0; m < 4; ++m) _Pragma("unroll") for (int n = 0; n < 2; ++n) _Pragma("unroll") for (int k = 0; k < 2; ++k) \
;         acc[ai][bj][m][n] = __builtin_amdgcn_mfma_f32_16x16x32_bf16(Bt[n][k], At[m][k], acc[ai][bj][m][n], 0, 0, 0); __builtin_amdgcn_s_setprio(0); } while (0)
; #define PG8_WAIT_V(n) asm volatile("s_waitcnt vmcnt(" #n ")" ::: "memory")
; #define PG8_WAIT_L(n) asm volatile("s_waitcnt lgkmcnt(" #n ")" ::: "memory")
; #define PG8_BAR __builtin_amdgcn_s_barrier()
; #define PG8_SCHED __builtin_amdgcn_sched_barrier(0)
; template <class EpiT, class Sched>
; __device__ __forceinline__ void gemm_phase(LAS unsigned char* lds, const Gemm g, const Sched& S, const EpiT& E, int wv) {
;     ...
;             PG8_LDA(At, 1, 1); PG8_STAGE(PG8_SB(1, 0), b3, voffB); PG8_STAGE(PG8_SB(1, 1), b3 + hstepB, voffB); PG8_STAGE(PG8_SA(1, 0), a3, voffA);
;             PG8_WAIT_V(8); PG8_WAIT_L(0); PG8_BAR; PG8_MMA(1, 0, At, B0); PG8_MMA(1, 1, At, B1); PG8_BAR; PG8_SCHED;
;         }
	s_add_i32 s4, s11, s49
	v_lshl_add_u64 v[216:217], v[216:217], 0, s[92:93]
	s_mov_b32 m0, s4
	ds_read_b128 v[172:175], v159 offset:49152
	ds_read_b128 v[176:179], v159 offset:50176
	ds_read_b128 v[180:183], v159 offset:51200
	ds_read_b128 v[184:187], v159 offset:52224
	ds_read_b128 v[188:191], v159 offset:53248
	ds_read_b128 v[204:207], v159 offset:54272
	ds_read_b128 v[208:211], v159 offset:55296
	ds_read_b128 v[212:215], v159 offset:56320
	global_load_lds_dwordx4 v[216:217], off
	v_lshl_add_u64 v[216:217], v[218:219], 0, s[92:93]
	s_add_i32 m0, s4, 0x2000
	s_add_i32 s4, s33, s49
	global_load_lds_dwordx4 v[216:217], off
	v_lshl_add_u64 v[216:217], v[220:221], 0, s[92:93]
	s_mov_b32 m0, s4
	s_nop 0
	global_load_lds_dwordx4 v[216:217], off
	v_lshl_add_u64 v[216:217], v[222:223], 0, s[92:93]
	s_add_i32 m0, s4, 0x2000
	s_nop 0
	global_load_lds_dwordx4 v[216:217], off
	v_lshl_add_u64 v[216:217], v[232:233], 0, s[92:93]
	s_mov_b32 m0, s54
	s_nop 0
	global_load_lds_dwordx4 v[216:217], off
	v_lshl_add_u64 v[216:217], v[234:235], 0, s[92:93]
	s_mov_b32 m0, s55
	s_nop 0
	global_load_lds_dwordx4 v[216:217], off
	s_waitcnt vmcnt(8)
	s_waitcnt lgkmcnt(0)
	s_barrier
	s_setprio 1
	v_mfma_f32_16x16x32_bf16 v[92:95], v[128:131], v[172:175], v[92:95]
	v_mfma_f32_16x16x32_bf16 v[88:91], v[146:149], v[172:175], v[88:91]
	v_mfma_f32_16x16x32_bf16 v[84:87], v[128:131], v[180:183], v[84:87]
	v_mfma_f32_16x16x32_bf16 v[80:83], v[146:149], v[180:183], v[80:83]
	v_mfma_f32_16x16x32_bf16 v[76:79], v[128:131], v[188:191], v[76:79]
	v_mfma_f32_16x16x32_bf16 v[72:75], v[146:149], v[188:191], v[72:75]
	v_mfma_f32_16x16x32_bf16 v[68:71], v[128:131], v[208:211], v[68:71]
	v_mfma_f32_16x16x32_bf16 v[64:67], v[146:149], v[208:211], v[64:67]
	v_mfma_f32_16x16x32_bf16 v[92:95], v[142:145], v[176:179], v[92:95]
	v_mfma_f32_16x16x32_bf16 v[88:91], v[150:153], v[176:179], v[88:91]
	v_mfma_f32_16x16x32_bf16 v[84:87], v[142:145], v[184:187], v[84:87]
	v_mfma_f32_16x16x32_bf16 v[80:83], v[150:153], v[184:187], v[80:83]
	v_mfma_f32_16x16x32_bf16 v[76:79], v[142:145], v[204:207], v[76:79]
	v_mfma_f32_16x16x32_bf16 v[72:75], v[150:153], v[204:207], v[72:75]
	v_mfma_f32_16x16x32_bf16 v[68:71], v[142:145], v[212:215], v[68:71]
	v_mfma_f32_16x16x32_bf16 v[64:67], v[150:153], v[212:215], v[64:67]
	s_setprio 0
	s_setprio 1
	v_mfma_f32_16x16x32_bf16 v[28:31], v[154:157], v[172:175], v[28:31]
	v_mfma_f32_16x16x32_bf16 v[24:27], v[164:167], v[172:175], v[24:27]
	v_mfma_f32_16x16x32_bf16 v[20:23], v[154:157], v[180:183], v[20:23]
	v_mfma_f32_16x16x32_bf16 v[16:19], v[164:167], v[180:183], v[16:19]
	v_mfma_f32_16x16x32_bf16 v[12:15], v[154:157], v[188:191], v[12:15]
	v_mfma_f32_16x16x32_bf16 v[8:11], v[164:167], v[188:191], v[8:11]
	v_mfma_f32_16x16x32_bf16 v[4:7], v[154:157], v[208:211], v[4:7]
	v_mfma_f32_16x16x32_bf16 v[0:3], v[164:167], v[208:211], v[0:3]
	v_mfma_f32_16x16x32_bf16 v[28:31], v[160:163], v[176:179], v[28:31]
	v_mfma_f32_16x16x32_bf16 v[24:27], v[168:171], v[176:179], v[24:27]
	v_mfma_f32_16x16x32_bf16 v[20:23], v[160:163], v[184:187], v[20:23]
	v_mfma_f32_16x16x32_bf16 v[16:19], v[168:171], v[184:187], v[16:19]
	v_mfma_f32_16x16x32_bf16 v[12:15], v[160:163], v[204:207], v[12:15]
	v_mfma_f32_16x16x32_bf16 v[8:11], v[168:171], v[204:207], v[8:11]
	v_mfma_f32_16x16x32_bf16 v[4:7], v[160:163], v[212:215], v[4:7]
	v_mfma_f32_16x16x32_bf16 v[0:3], v[168:171], v[212:215], v[0:3]
	s_setprio 0
	s_barrier
	s_add_u32 s0, s0, 0x100
	s_addc_u32 s1, s1, 0
	s_add_u32 s6, s6, 0x100
	s_addc_u32 s7, s7, 0
	s_cmp_ge_i32 s9, s57
	s_mov_b32 s4, s9
	s_cbranch_scc0 .LBB0_472

; #define PG8_STAGE(bufoff, gbase, voff) do { _Pragma("unroll") for (int _i = 0; _i < 2; ++_i) \
;         __builtin_amdgcn_global_load_lds((const unsigned*)((const char*)(gbase) + (voff)[_i]), (LAS unsigned*)(lds + (bufoff) + ldsw + _i * 8192), 16, 0, 0); } while (0)
; #define PG8_LDA(dst, b, h) do { _Pragma("unroll") for (int m = 0; m < 4; ++m) _Pragma("unroll") for (int k = 0; k < 2; ++k) dst[m][k] = *(const LAS bf16x8*)(lds + PG8_SA(b, h) + aoff + m * 2048 + k * 1024); } while (0)
; #define PG8_LDB(dst, b, h) do { _Pragma("unroll") for (int n = 0; n < 2; ++n) _Pragma("unroll") for (int k = 0; k < 2; ++k) dst[n][k] = *(const LAS bf16x8*)(lds + PG8_SB(b, h) + boff + n * 2048 + k * 1024); } while (0)
; #define PG8_MMA(ai, bj, At, Bt) do { __builtin_amdgcn_s_setprio(1); _Pragma("unroll") for (int m = 0; m < 4; ++m) _Pragma("unroll") for (int n = 0; n < 2; ++n) _Pragma("unroll") for (int k = 0; k < 2; ++k) \
;         acc[ai][bj][m][n] = __builtin_amdgcn_mfma_f32_16x16x32_bf16(Bt[n][k], At[m][k], acc[ai][bj][m][n], 0, 0, 0); __builtin_amdgcn_s_setprio(0); } while (0)
; #define PG8_WAIT_V(n) asm volatile("s_waitcnt vmcnt(" #n ")" ::: "memory")
; #define PG8_WAIT_L(n) asm volatile("s_waitcnt lgkmcnt(" #n ")" ::: "memory")
; #define PG8_BAR __builtin_amdgcn_s_barrier()
; #define PG8_SCHED __builtin_amdgcn_sched_barrier(0)
; template <class EpiT, class Sched>
; __device__ __forceinline__ void gemm_phase(LAS unsigned char* lds, const Gemm g, const Sched& S, const EpiT& E, int wv) {
;     ...
;             const bool last = (t == nt - 2);
;             const char* a1 = cA + (size_t)(t + 1) * kstep;
;             const char* a2 = last ? nA : cA + (size_t)(t + 2) * kstep; const char* b2 = last ? nB : cB + (size_t)(t + 2) * kstep;
;             const char* a3 = a2 + kstep; const char* b3 = b2 + kstep;
;             PG8_LDB(B0, 0, 0); PG8_LDB(B1, 0, 1); PG8_SCHED; PG8_LDA(At, 0, 0); PG8_STAGE(PG8_SA(1, 1), a1 + hstepA, voffA);
;             PG8_WAIT_V(8); PG8_WAIT_L(0); PG8_BAR; PG8_MMA(0, 0, At, B0); PG8_MMA(0, 1, At, B1); PG8_BAR; PG8_SCHED;
;             PG8_LDA(At, 0, 1); PG8_STAGE(PG8_SB(0, 0), b2, voffB); PG8_STAGE(PG8_SB(0, 1), b2 + hstepB, voffB); PG8_STAGE(PG8_SA(0, 0), a2, voffA);
;             PG8_WAIT_V(8); PG8_WAIT_L(0); PG8_BAR; PG8_MMA(1, 0, At, B0); PG8_MMA(1, 1, At, B1); PG8_BAR; PG8_SCHED;
.LBB0_623:
	s_add_i32 s39, s4, 2
	s_add_u32 s63, s0, 0x80
	s_addc_u32 s5, s1, 0
	s_add_i32 s67, 0, 0x10000
	s_cmp_eq_u32 s53, s4
	s_cselect_b32 s5, s31, s5
	s_cselect_b32 s4, s30, s63
	s_cselect_b32 s65, s35, s37
	s_cselect_b32 s64, s34, s36
	s_add_i32 s63, 0, 0x14000
	ds_read_b128 v[128:131], v250
	ds_read_b128 v[132:135], v250 offset:1024
	ds_read_b128 v[136:139], v250 offset:2048
	ds_read_b128 v[150:153], v250 offset:3072
	ds_read_b128 v[154:157], v251
	ds_read_b128 v[160:163], v251 offset:1024
	ds_read_b128 v[164:167], v251 offset:2048
	ds_read_b128 v[168:171], v251 offset:3072
	v_lshl_add_u64 v[216:217], s[0:1], 0, v[146:147]
	s_add_i32 m0, s46, 0xc000
	ds_read_b128 v[172:175], v159
	ds_read_b128 v[176:179], v159 offset:1024
	ds_read_b128 v[180:183], v159 offset:2048
	ds_read_b128 v[184:187], v159 offset:3072
	ds_read_b128 v[188:191], v159 offset:4096
	ds_read_b128 v[204:207], v159 offset:5120
	ds_read_b128 v[208:211], v159 offset:6144
	ds_read_b128 v[212:215], v159 offset:7168
	global_load_lds_dwordx4 v[216:217], off
	v_lshl_add_u64 v[216:217], s[0:1], 0, v[148:149]
	s_add_i32 m0, s46, 0xe000
	s_nop 0
	global_load_lds_dwordx4 v[216:217], off
	s_waitcnt vmcnt(8)
	s_waitcnt lgkmcnt(0)
	s_barrier
	s_setprio 1
	v_mfma_f32_16x16x32_bf16 v[120:123], v[128:131], v[172:175], v[120:123]
	v_mfma_f32_16x16x32_bf16 v[124:127], v[136:139], v[172:175], v[124:127]
	v_mfma_f32_16x16x32_bf16 v[116:119], v[128:131], v[180:183], v[116:119]
	v_mfma_f32_16x16x32_bf16 v[112:115], v[136:139], v[180:183], v[112:115]
	v_mfma_f32_16x16x32_bf16 v[108:111], v[128:131], v[188:191], v[108:111]
	v_mfma_f32_16x16x32_bf16 v[104:107], v[136:139], v[188:191], v[104:107]
	v_mfma_f32_16x16x32_bf16 v[100:103], v[128:131], v[208:211], v[100:103]
	v_mfma_f32_16x16x32_bf16 v[96:99], v[136:139], v[208:211], v[96:99]
	v_mfma_f32_16x16x32_bf16 v[120:123], v[132:135], v[176:179], v[120:123]
	v_mfma_f32_16x16x32_bf16 v[124:127], v[150:153], v[176:179], v[124:127]
	v_mfma_f32_16x16x32_bf16 v[116:119], v[132:135], v[184:187], v[116:119]
	v_mfma_f32_16x16x32_bf16 v[112:115], v[150:153], v[184:187], v[112:115]
	v_mfma_f32_16x16x32_bf16 v[108:111], v[132:135], v[204:207], v[108:111]
	v_mfma_f32_16x16x32_bf16 v[104:107], v[150:153], v[204:207], v[104:107]
	v_mfma_f32_16x16x32_bf16 v[100:103], v[132:135], v[212:215], v[100:103]
	v_mfma_f32_16x16x32_bf16 v[96:99], v[150:153], v[212:215], v[96:99]
	s_setprio 0
	s_setprio 1
	v_mfma_f32_16x16x32_bf16 v[60:63], v[154:157], v[172:175], v[60:63]
	v_mfma_f32_16x16x32_bf16 v[56:59], v[164:167], v[172:175], v[56:59]
	v_mfma_f32_16x16x32_bf16 v[52:55], v[154:157], v[180:183], v[52:55]
	v_mfma_f32_16x16x32_bf16 v[48:51], v[164:167], v[180:183], v[48:51]
	v_mfma_f32_16x16x32_bf16 v[44:47], v[154:157], v[188:191], v[44:47]
	v_mfma_f32_16x16x32_bf16 v[40:43], v[164:167], v[188:191], v[40:43]
	v_mfma_f32_16x16x32_bf16 v[36:39], v[154:157], v[208:211], v[36:39]
	v_mfma_f32_16x16x32_bf16 v[32:35], v[164:167], v[208:211], v[32:35]
	v_mfma_f32_16x16x32_bf16 v[60:63], v[160:163], v[176:179], v[60:63]
	v_mfma_f32_16x16x32_bf16 v[56:59], v[168:171], v[176:179], v[56:59]
	v_mfma_f32_16x16x32_bf16 v[52:55], v[160:163], v[184:187], v[52:55]
	v_mfma_f32_16x16x32_bf16 v[48:51], v[168:171], v[184:187], v[48:51]
	v_mfma_f32_16x16x32_bf16 v[44:47], v[160:163], v[204:207], v[44:47]
	v_mfma_f32_16x16x32_bf16 v[40:43], v[168:171], v[204:207], v[40:43]
	v_mfma_f32_16x16x32_bf16 v[36:39], v[160:163], v[212:215], v[36:39]
	v_mfma_f32_16x16x32_bf16 v[32:35], v[168:171], v[212:215], v[32:35]
	s_setprio 0
	s_barrier
	s_add_i32 s67, s67, s45
	v_lshl_add_u64 v[216:217], s[64:65], 0, v[192:193]
	s_mov_b32 m0, s67
	ds_read_b128 v[172:175], v159 offset:16384
	ds_read_b128 v[176:179], v159 offset:17408
	ds_read_b128 v[180:183], v159 offset:18432
	ds_read_b128 v[184:187], v159 offset:19456
	ds_read_b128 v[188:191], v159 offset:20480
	ds_read_b128 v[204:207], v159 offset:21504
	ds_read_b128 v[208:211], v159 offset:22528
	ds_read_b128 v[212:215], v159 offset:23552
	global_load_lds_dwordx4 v[216:217], off
	s_add_i32 m0, s67, 0x2000
	v_lshl_add_u64 v[218:219], s[64:65], 0, v[144:145]
	s_add_u32 s64, s64, s6
	s_addc_u32 s65, s65, s7
	s_add_i32 s63, s63, s45
	global_load_lds_dwordx4 v[218:219], off
	v_lshl_add_u64 v[220:221], s[64:65], 0, v[192:193]
	s_mov_b32 m0, s63
	v_lshl_add_u64 v[222:223], s[64:65], 0, v[144:145]
	global_load_lds_dwordx4 v[220:221], off
	s_add_i32 m0, s63, 0x2000
	v_lshl_add_u64 v[232:233], s[4:5], 0, v[140:141]
	global_load_lds_dwordx4 v[222:223], off
	s_mov_b32 m0, s46
	v_lshl_add_u64 v[234:235], s[4:5], 0, v[142:143]
	global_load_lds_dwordx4 v[232:233], off
	s_mov_b32 m0, s47
	s_nop 0
	global_load_lds_dwordx4 v[234:235], off
	s_waitcnt vmcnt(8)
	s_waitcnt lgkmcnt(0)
	s_barrier
; #define PG8_STAGE(bufoff, gbase, voff) do { _Pragma("unroll") for (int _i = 0; _i < 2; ++_i) \
;         __builtin_amdgcn_global_load_lds((const unsigned*)((const char*)(gbase) + (voff)[_i]), (LAS unsigned*)(lds + (bufoff) + ldsw + _i * 8192), 16, 0, 0); } while (0)
; #define PG8_LDA(dst, b, h) do { _Pragma("unroll") for (int m = 0; m < 4; ++m) _Pragma("unroll") for (int k = 0; k < 2; ++k) dst[m][k] = *(const LAS bf16x8*)(lds + PG8_SA(b, h) + aoff + m * 2048 + k * 1024); } while (0)
; #define PG8_LDB(dst, b, h) do { _Pragma("unroll") for (int n = 0; n < 2; ++n) _Pragma("unroll") for (int k = 0; k < 2; ++k) dst[n][k] = *(const LAS bf16x8*)(lds + PG8_SB(b, h) + boff + n * 2048 + k * 1024); } while (0)
; #define PG8_MMA(ai, bj, At, Bt) do { __builtin_amdgcn_s_setprio(1); _Pragma("unroll") for (int m = 0; m < 4; ++m) _Pragma("unroll") for (int n = 0; n < 2; ++n) _Pragma("unroll") for (int k = 0; k < 2; ++k) \
;         acc[ai][bj][m][n] = __builtin_amdgcn_mfma_f32_16x16x32_bf16(Bt[n][k], At[m][k], acc[ai][bj][m][n], 0, 0, 0); __builtin_amdgcn_s_setprio(0); } while (0)
; #define PG8_WAIT_V(n) asm volatile("s_waitcnt vmcnt(" #n ")" ::: "memory")
; #define PG8_WAIT_L(n) asm volatile("s_waitcnt lgkmcnt(" #n ")" ::: "memory")
; #define PG8_BAR __builtin_amdgcn_s_barrier()
; #define PG8_SCHED __builtin_amdgcn_sched_barrier(0)
; template <class EpiT, class Sched>
; __device__ __forceinline__ void gemm_phase(LAS unsigned char* lds, const Gemm g, const Sched& S, const EpiT& E, int wv) {
;     ...
;             PG8_WAIT_V(8); PG8_WAIT_L(0); PG8_BAR; PG8_MMA(1, 0, At, B0); PG8_MMA(1, 1, At, B1); PG8_BAR; PG8_SCHED;
;             PG8_LDB(B0, 1, 0); PG8_LDB(B1, 1, 1); PG8_SCHED; PG8_LDA(At, 1, 0); PG8_STAGE(PG8_SA(0, 1), a2 + hstepA, voffA);
;             PG8_WAIT_V(8); PG8_WAIT_L(0); PG8_BAR; PG8_MMA(0, 0, At, B0); PG8_MMA(0, 1, At, B1); PG8_BAR; PG8_SCHED;
	s_setprio 1
	v_mfma_f32_16x16x32_bf16 v[92:95], v[128:131], v[172:175], v[92:95]
	v_mfma_f32_16x16x32_bf16 v[88:91], v[136:139], v[172:175], v[88:91]
	v_mfma_f32_16x16x32_bf16 v[84:87], v[128:131], v[180:183], v[84:87]
	v_mfma_f32_16x16x32_bf16 v[80:83], v[136:139], v[180:183], v[80:83]
	v_mfma_f32_16x16x32_bf16 v[76:79], v[128:131], v[188:191], v[76:79]
	v_mfma_f32_16x16x32_bf16 v[72:75], v[136:139], v[188:191], v[72:75]
	v_mfma_f32_16x16x32_bf16 v[68:71], v[128:131], v[208:211], v[68:71]
	v_mfma_f32_16x16x32_bf16 v[64:67], v[136:139], v[208:211], v[64:67]
	v_mfma_f32_16x16x32_bf16 v[92:95], v[132:135], v[176:179], v[92:95]
	v_mfma_f32_16x16x32_bf16 v[88:91], v[150:153], v[176:179], v[88:91]
	v_mfma_f32_16x16x32_bf16 v[84:87], v[132:135], v[184:187], v[84:87]
	v_mfma_f32_16x16x32_bf16 v[80:83], v[150:153], v[184:187], v[80:83]
	v_mfma_f32_16x16x32_bf16 v[76:79], v[132:135], v[204:207], v[76:79]
	v_mfma_f32_16x16x32_bf16 v[72:75], v[150:153], v[204:207], v[72:75]
	v_mfma_f32_16x16x32_bf16 v[68:71], v[132:135], v[212:215], v[68:71]
	v_mfma_f32_16x16x32_bf16 v[64:67], v[150:153], v[212:215], v[64:67]
	s_setprio 0
	s_setprio 1
	v_mfma_f32_16x16x32_bf16 v[28:31], v[154:157], v[172:175], v[28:31]
	v_mfma_f32_16x16x32_bf16 v[24:27], v[164:167], v[172:175], v[24:27]
	v_mfma_f32_16x16x32_bf16 v[20:23], v[154:157], v[180:183], v[20:23]
	v_mfma_f32_16x16x32_bf16 v[16:19], v[164:167], v[180:183], v[16:19]
	v_mfma_f32_16x16x32_bf16 v[12:15], v[154:157], v[188:191], v[12:15]
	v_mfma_f32_16x16x32_bf16 v[8:11], v[164:167], v[188:191], v[8:11]
	v_mfma_f32_16x16x32_bf16 v[4:7], v[154:157], v[208:211], v[4:7]
	v_mfma_f32_16x16x32_bf16 v[0:3], v[164:167], v[208:211], v[0:3]
	v_mfma_f32_16x16x32_bf16 v[28:31], v[160:163], v[176:179], v[28:31]
	v_mfma_f32_16x16x32_bf16 v[24:27], v[168:171], v[176:179], v[24:27]
	v_mfma_f32_16x16x32_bf16 v[20:23], v[160:163], v[184:187], v[20:23]
	v_mfma_f32_16x16x32_bf16 v[16:19], v[168:171], v[184:187], v[16:19]
	v_mfma_f32_16x16x32_bf16 v[12:15], v[160:163], v[204:207], v[12:15]
	v_mfma_f32_16x16x32_bf16 v[8:11], v[168:171], v[204:207], v[8:11]
	v_mfma_f32_16x16x32_bf16 v[4:7], v[160:163], v[212:215], v[4:7]
	v_mfma_f32_16x16x32_bf16 v[0:3], v[168:171], v[212:215], v[0:3]
	s_setprio 0
	s_barrier
	s_add_i32 s63, 0, 0x18000
	s_add_i32 s64, 0, 0x1c000
	ds_read_b128 v[128:131], v252
	ds_read_b128 v[132:135], v252 offset:1024
	ds_read_b128 v[136:139], v252 offset:2048
	ds_read_b128 v[150:153], v252 offset:3072
	ds_read_b128 v[154:157], v253
	ds_read_b128 v[160:163], v253 offset:1024
	ds_read_b128 v[164:167], v253 offset:2048
	ds_read_b128 v[168:171], v253 offset:3072
	s_add_u32 s4, s4, s6
	s_addc_u32 s5, s5, s7
	s_mov_b32 m0, s48
	v_lshl_add_u64 v[240:241], s[4:5], 0, v[140:141]
	ds_read_b128 v[172:175], v159 offset:32768
	ds_read_b128 v[176:179], v159 offset:33792
	ds_read_b128 v[180:183], v159 offset:34816
	ds_read_b128 v[184:187], v159 offset:35840
	ds_read_b128 v[188:191], v159 offset:36864
	ds_read_b128 v[204:207], v159 offset:37888
	ds_read_b128 v[208:211], v159 offset:38912
	ds_read_b128 v[212:215], v159 offset:39936
	global_load_lds_dwordx4 v[240:241], off
	v_lshl_add_u64 v[240:241], s[4:5], 0, v[142:143]
	s_mov_b32 m0, s49
	s_nop 0
	global_load_lds_dwordx4 v[240:241], off
	s_waitcnt vmcnt(8)
	s_waitcnt lgkmcnt(0)
	s_barrier
	s_setprio 1
	v_mfma_f32_16x16x32_bf16 v[120:123], v[128:131], v[172:175], v[120:123]
	v_mfma_f32_16x16x32_bf16 v[124:127], v[136:139], v[172:175], v[124:127]
	v_mfma_f32_16x16x32_bf16 v[116:119], v[128:131], v[180:183], v[116:119]
	v_mfma_f32_16x16x32_bf16 v[112:115], v[136:139], v[180:183], v[112:115]
	v_mfma_f32_16x16x32_bf16 v[108:111], v[128:131], v[188:191], v[108:111]
	v_mfma_f32_16x16x32_bf16 v[104:107], v[136:139], v[188:191], v[104:107]
	v_mfma_f32_16x16x32_bf16 v[100:103], v[128:131], v[208:211], v[100:103]
	v_mfma_f32_16x16x32_bf16 v[96:99], v[136:139], v[208:211], v[96:99]
	v_mfma_f32_16x16x32_bf16 v[120:123], v[132:135], v[176:179], v[120:123]
	v_mfma_f32_16x16x32_bf16 v[124:127], v[150:153], v[176:179], v[124:127]
	v_mfma_f32_16x16x32_bf16 v[116:119], v[132:135], v[184:187], v[116:119]
	v_mfma_f32_16x16x32_bf16 v[112:115], v[150:153], v[184:187], v[112:115]
	v_mfma_f32_16x16x32_bf16 v[108:111], v[132:135], v[204:207], v[108:111]
	v_mfma_f32_16x16x32_bf16 v[104:107], v[150:153], v[204:207], v[104:107]
	v_mfma_f32_16x16x32_bf16 v[100:103], v[132:135], v[212:215], v[100:103]
	v_mfma_f32_16x16x32_bf16 v[96:99], v[150:153], v[212:215], v[96:99]
	s_setprio 0
	s_setprio 1
	v_mfma_f32_16x16x32_bf16 v[60:63], v[154:157], v[172:175], v[60:63]
	v_mfma_f32_16x16x32_bf16 v[56:59], v[164:167], v[172:175], v[56:59]
	v_mfma_f32_16x16x32_bf16 v[52:55], v[154:157], v[180:183], v[52:55]
	v_mfma_f32_16x16x32_bf16 v[48:51], v[164:167], v[180:183], v[48:51]
	v_mfma_f32_16x16x32_bf16 v[44:47], v[154:157], v[188:191], v[44:47]
	v_mfma_f32_16x16x32_bf16 v[40:43], v[164:167], v[188:191], v[40:43]
	v_mfma_f32_16x16x32_bf16 v[36:39], v[154:157], v[208:211], v[36:39]
	v_mfma_f32_16x16x32_bf16 v[32:35], v[164:167], v[208:211], v[32:35]
	v_mfma_f32_16x16x32_bf16 v[60:63], v[160:163], v[176:179], v[60:63]
	v_mfma_f32_16x16x32_bf16 v[56:59], v[168:171], v[176:179], v[56:59]
	v_mfma_f32_16x16x32_bf16 v[52:55], v[160:163], v[184:187], v[52:55]
	v_mfma_f32_16x16x32_bf16 v[48:51], v[168:171], v[184:187], v[48:51]
	v_mfma_f32_16x16x32_bf16 v[44:47], v[160:163], v[204:207], v[44:47]
	v_mfma_f32_16x16x32_bf16 v[40:43], v[168:171], v[204:207], v[40:43]
	v_mfma_f32_16x16x32_bf16 v[36:39], v[160:163], v[212:215], v[36:39]
	v_mfma_f32_16x16x32_bf16 v[32:35], v[168:171], v[212:215], v[32:35]
	s_setprio 0
	s_barrier
; #define PG8_STAGE(bufoff, gbase, voff) do { _Pragma("unroll") for (int _i = 0; _i < 2; ++_i) \
;         __builtin_amdgcn_global_load_lds((const unsigned*)((const char*)(gbase) + (voff)[_i]), (LAS unsigned*)(lds + (bufoff) + ldsw + _i * 8192), 16, 0, 0); } while (0)
; #define PG8_LDA(dst, b, h) do { _Pragma("unroll") for (int m = 0; m < 4; ++m) _Pragma("unroll") for (int k = 0; k < 2; ++k) dst[m][k] = *(const LAS bf16x8*)(lds + PG8_SA(b, h) + aoff + m * 2048 + k * 1024); } while (0)
; #define PG8_MMA(ai, bj, At, Bt) do { __builtin_amdgcn_s_setprio(1); _Pragma("unroll") for (int m = 0; m < 4; ++m) _Pragma("unroll") for (int n = 0; n < 2; ++n) _Pragma("unroll") for (int k = 0; k < 2; ++k) \
;         acc[ai][bj][m][n] = __builtin_amdgcn_mfma_f32_16x16x32_bf16(Bt[n][k], At[m][k], acc[ai][bj][m][n], 0, 0, 0); __builtin_amdgcn_s_setprio(0); } while (0)
; #define PG8_WAIT_V(n) asm volatile("s_waitcnt vmcnt(" #n ")" ::: "memory")
; #define PG8_WAIT_L(n) asm volatile("s_waitcnt lgkmcnt(" #n ")" ::: "memory")
; #define PG8_BAR __builtin_amdgcn_s_barrier()
; #define PG8_SCHED __builtin_amdgcn_sched_barrier(0)
; template <class EpiT, class Sched>
; __device__ __forceinline__ void gemm_phase(LAS unsigned char* lds, const Gemm g, const Sched& S, const EpiT& E, int wv) {
;     ...
;             PG8_LDA(At, 1, 1); PG8_STAGE(PG8_SB(1, 0), b3, voffB); PG8_STAGE(PG8_SB(1, 1), b3 + hstepB, voffB); PG8_STAGE(PG8_SA(1, 0), a3, voffA);
;             PG8_WAIT_V(8); PG8_WAIT_L(0); PG8_BAR; PG8_MMA(1, 0, At, B0); PG8_MMA(1, 1, At, B1); PG8_BAR; PG8_SCHED;
;         }
	s_add_i32 s4, s63, s45
	v_lshl_add_u64 v[216:217], v[216:217], 0, s[92:93]
	s_mov_b32 m0, s4
	ds_read_b128 v[172:175], v159 offset:49152
	ds_read_b128 v[176:179], v159 offset:50176
	ds_read_b128 v[180:183], v159 offset:51200
	ds_read_b128 v[184:187], v159 offset:52224
	ds_read_b128 v[188:191], v159 offset:53248
	ds_read_b128 v[204:207], v159 offset:54272
	ds_read_b128 v[208:211], v159 offset:55296
	ds_read_b128 v[212:215], v159 offset:56320
	global_load_lds_dwordx4 v[216:217], off
	v_lshl_add_u64 v[216:217], v[218:219], 0, s[92:93]
	s_add_i32 m0, s4, 0x2000
	s_add_i32 s4, s64, s45
	global_load_lds_dwordx4 v[216:217], off
	v_lshl_add_u64 v[216:217], v[220:221], 0, s[92:93]
	s_mov_b32 m0, s4
	s_nop 0
	global_load_lds_dwordx4 v[216:217], off
	v_lshl_add_u64 v[216:217], v[222:223], 0, s[92:93]
	s_add_i32 m0, s4, 0x2000
	s_nop 0
	global_load_lds_dwordx4 v[216:217], off
	v_lshl_add_u64 v[216:217], v[232:233], 0, s[92:93]
	s_mov_b32 m0, s50
	s_nop 0
	global_load_lds_dwordx4 v[216:217], off
	v_lshl_add_u64 v[216:217], v[234:235], 0, s[92:93]
	s_mov_b32 m0, s51
	s_nop 0
	global_load_lds_dwordx4 v[216:217], off
	s_waitcnt vmcnt(8)
	s_waitcnt lgkmcnt(0)
	s_barrier
	s_setprio 1
	v_mfma_f32_16x16x32_bf16 v[92:95], v[128:131], v[172:175], v[92:95]
	v_mfma_f32_16x16x32_bf16 v[88:91], v[136:139], v[172:175], v[88:91]
	v_mfma_f32_16x16x32_bf16 v[84:87], v[128:131], v[180:183], v[84:87]
	v_mfma_f32_16x16x32_bf16 v[80:83], v[136:139], v[180:183], v[80:83]
	v_mfma_f32_16x16x32_bf16 v[76:79], v[128:131], v[188:191], v[76:79]
	v_mfma_f32_16x16x32_bf16 v[72:75], v[136:139], v[188:191], v[72:75]
	v_mfma_f32_16x16x32_bf16 v[68:71], v[128:131], v[208:211], v[68:71]
	v_mfma_f32_16x16x32_bf16 v[64:67], v[136:139], v[208:211], v[64:67]
	v_mfma_f32_16x16x32_bf16 v[92:95], v[132:135], v[176:179], v[92:95]
	v_mfma_f32_16x16x32_bf16 v[88:91], v[150:153], v[176:179], v[88:91]
	v_mfma_f32_16x16x32_bf16 v[84:87], v[132:135], v[184:187], v[84:87]
	v_mfma_f32_16x16x32_bf16 v[80:83], v[150:153], v[184:187], v[80:83]
	v_mfma_f32_16x16x32_bf16 v[76:79], v[132:135], v[204:207], v[76:79]
	v_mfma_f32_16x16x32_bf16 v[72:75], v[150:153], v[204:207], v[72:75]
	v_mfma_f32_16x16x32_bf16 v[68:71], v[132:135], v[212:215], v[68:71]
	v_mfma_f32_16x16x32_bf16 v[64:67], v[150:153], v[212:215], v[64:67]
	s_setprio 0
	s_setprio 1
	v_mfma_f32_16x16x32_bf16 v[28:31], v[154:157], v[172:175], v[28:31]
	v_mfma_f32_16x16x32_bf16 v[24:27], v[164:167], v[172:175], v[24:27]
	v_mfma_f32_16x16x32_bf16 v[20:23], v[154:157], v[180:183], v[20:23]
	v_mfma_f32_16x16x32_bf16 v[16:19], v[164:167], v[180:183], v[16:19]
	v_mfma_f32_16x16x32_bf16 v[12:15], v[154:157], v[188:191], v[12:15]
	v_mfma_f32_16x16x32_bf16 v[8:11], v[164:167], v[188:191], v[8:11]
	v_mfma_f32_16x16x32_bf16 v[4:7], v[154:157], v[208:211], v[4:7]
	v_mfma_f32_16x16x32_bf16 v[0:3], v[164:167], v[208:211], v[0:3]
	v_mfma_f32_16x16x32_bf16 v[28:31], v[160:163], v[176:179], v[28:31]
	v_mfma_f32_16x16x32_bf16 v[24:27], v[168:171], v[176:179], v[24:27]
	v_mfma_f32_16x16x32_bf16 v[20:23], v[160:163], v[184:187], v[20:23]
	v_mfma_f32_16x16x32_bf16 v[16:19], v[168:171], v[184:187], v[16:19]
	v_mfma_f32_16x16x32_bf16 v[12:15], v[160:163], v[204:207], v[12:15]
	v_mfma_f32_16x16x32_bf16 v[8:11], v[168:171], v[204:207], v[8:11]
	v_mfma_f32_16x16x32_bf16 v[4:7], v[160:163], v[212:215], v[4:7]
	v_mfma_f32_16x16x32_bf16 v[0:3], v[168:171], v[212:215], v[0:3]
	s_setprio 0
	s_barrier
	s_add_u32 s0, s0, 0x100
	s_addc_u32 s1, s1, 0
	s_add_u32 s36, s36, 0x100
	s_addc_u32 s37, s37, 0
	s_cmp_ge_i32 s39, s52
	s_mov_b32 s4, s39
	s_cbranch_scc0 .LBB0_623
	v_readlane_b32 s67, v255, 5

.LBB0_937:
	v_exp_f32_e32 v80, v80
	v_exp_f32_e32 v81, v81
	v_exp_f32_e32 v82, v82
	v_exp_f32_e32 v83, v83
	v_exp_f32_e32 v84, v84
	v_exp_f32_e32 v85, v85
	v_exp_f32_e32 v86, v86
	v_exp_f32_e32 v87, v87
	v_exp_f32_e32 v206, v64
	v_exp_f32_e32 v207, v65
	v_exp_f32_e32 v208, v66
	v_exp_f32_e32 v209, v67
	v_cvt_pk_bf16_f32 v64, v80, v81
	v_cvt_pk_bf16_f32 v65, v82, v83
	v_cvt_pk_bf16_f32 v66, v84, v85
	v_cvt_pk_bf16_f32 v67, v86, v87
	s_waitcnt lgkmcnt(0)
	v_exp_f32_e32 v88, v88
	v_exp_f32_e32 v89, v89
	v_mfma_f32_32x32x16_bf16 v[0:15], v[164:167], v[64:67], v[0:15]
	v_exp_f32_e32 v90, v90
	v_exp_f32_e32 v91, v91
	v_exp_f32_e32 v92, v92
	v_exp_f32_e32 v93, v93
	v_exp_f32_e32 v94, v94
	v_exp_f32_e32 v95, v95
	v_exp_f32_e32 v210, v68
	v_mfma_f32_32x32x16_bf16 v[16:31], v[148:151], v[64:67], v[16:31]
	v_exp_f32_e32 v211, v69
	v_exp_f32_e32 v212, v70
	v_exp_f32_e32 v213, v71
	v_cvt_pk_bf16_f32 v68, v88, v89
	v_cvt_pk_bf16_f32 v69, v90, v91
	v_cvt_pk_bf16_f32 v70, v92, v93
	v_cvt_pk_bf16_f32 v71, v94, v95
	v_exp_f32_e32 v214, v72
	v_mfma_f32_32x32x16_bf16 v[0:15], v[160:163], v[68:71], v[0:15]
	v_exp_f32_e32 v215, v73
	v_exp_f32_e32 v160, v74
	v_exp_f32_e32 v161, v75
	v_cvt_pk_bf16_f32 v72, v206, v207
	v_cvt_pk_bf16_f32 v73, v208, v209
	v_cvt_pk_bf16_f32 v74, v210, v211
	v_cvt_pk_bf16_f32 v75, v212, v213
	v_mfma_f32_32x32x16_bf16 v[16:31], v[144:147], v[68:71], v[16:31]
	v_add_f32_e64 v64, v206, v80
	v_add_f32_e64 v65, v207, v81
	v_exp_f32_e32 v162, v76
	v_add_f32_e32 v64, v82, v64
	v_add_f32_e32 v65, v83, v65
	v_exp_f32_e32 v163, v77
	v_add_f32_e32 v64, v208, v64
	v_add_f32_e32 v65, v209, v65
	v_cvt_pk_bf16_f32 v76, v214, v215
	v_add_f32_e32 v64, v84, v64
	v_add_f32_e32 v65, v85, v65
	v_mfma_f32_32x32x16_bf16 v[0:15], v[156:159], v[72:75], v[0:15]
	v_exp_f32_e32 v156, v78
	v_exp_f32_e32 v157, v79
	v_add_f32_e32 v64, v210, v64
	v_add_f32_e32 v65, v211, v65
	v_cvt_pk_bf16_f32 v77, v160, v161
	v_add_f32_e32 v64, v86, v64
	v_add_f32_e32 v65, v87, v65
	v_cvt_pk_bf16_f32 v78, v162, v163
	v_add_f32_e32 v64, v212, v64
	v_add_f32_e32 v65, v213, v65
	v_mfma_f32_32x32x16_bf16 v[16:31], v[140:143], v[72:75], v[16:31]
	v_add_f32_e64 v64, v88, v64
	v_add_f32_e64 v65, v89, v65
	v_cvt_pk_bf16_f32 v79, v156, v157
	v_add_f32_e64 v64, v214, v64
	v_add_f32_e64 v65, v215, v65
	s_add_i32 s17, s17, 0x8000
	v_add_f32_e32 v64, v90, v64
	v_add_f32_e32 v65, v91, v65
	v_lshl_add_u64 v[170:171], v[170:171], 0, s[94:95]
	v_add_f32_e32 v64, v160, v64
	v_add_f32_e32 v65, v161, v65
	v_mfma_f32_32x32x16_bf16 v[0:15], v[152:155], v[76:79], v[0:15]
	v_add_f32_e64 v64, v92, v64
	v_add_f32_e64 v65, v93, v65
	v_lshl_add_u64 v[172:173], v[172:173], 0, s[96:97]
	v_add_f32_e64 v64, v162, v64
	v_add_f32_e64 v65, v163, v65
	s_cmp_lg_u32 s17, 0x118000
	v_add_f32_e32 v64, v94, v64
	v_add_f32_e32 v65, v95, v65
	v_lshl_add_u64 v[174:175], v[174:175], 0, s[96:97]
	v_add_f32_e32 v64, v156, v64
	v_add_f32_e32 v65, v157, v65
	v_mfma_f32_32x32x16_bf16 v[16:31], v[136:139], v[76:79], v[16:31]
	v_add_f32_e32 v64, v64, v65
	v_add_f32_e32 v136, v179, v64
	s_cbranch_scc0 .LBB0_939
	v_mov_b32_e32 v177, v136
	s_branch .LBB0_926

; #define PG8_STAGE(bufoff, gbase, voff) do { _Pragma("unroll") for (int _i = 0; _i < 2; ++_i) \
;         __builtin_amdgcn_global_load_lds((const unsigned*)((const char*)(gbase) + (voff)[_i]), (LAS unsigned*)(lds + (bufoff) + ldsw + _i * 8192), 16, 0, 0); } while (0)
; #define PG8_LDA(dst, b, h) do { _Pragma("unroll") for (int m = 0; m < 4; ++m) _Pragma("unroll") for (int k = 0; k < 2; ++k) dst[m][k] = *(const LAS bf16x8*)(lds + PG8_SA(b, h) + aoff + m * 2048 + k * 1024); } while (0)
; #define PG8_LDB(dst, b, h) do { _Pragma("unroll") for (int n = 0; n < 2; ++n) _Pragma("unroll") for (int k = 0; k < 2; ++k) dst[n][k] = *(const LAS bf16x8*)(lds + PG8_SB(b, h) + boff + n * 2048 + k * 1024); } while (0)
; #define PG8_MMA(ai, bj, At, Bt) do { __builtin_amdgcn_s_setprio(1); _Pragma("unroll") for (int m = 0; m < 4; ++m) _Pragma("unroll") for (int n = 0; n < 2; ++n) _Pragma("unroll") for (int k = 0; k < 2; ++k) \
;         acc[ai][bj][m][n] = __builtin_amdgcn_mfma_f32_16x16x32_bf16(Bt[n][k], At[m][k], acc[ai][bj][m][n], 0, 0, 0); __builtin_amdgcn_s_setprio(0); } while (0)
; #define PG8_WAIT_V(n) asm volatile("s_waitcnt vmcnt(" #n ")" ::: "memory")
; #define PG8_WAIT_L(n) asm volatile("s_waitcnt lgkmcnt(" #n ")" ::: "memory")
; #define PG8_BAR __builtin_amdgcn_s_barrier()
; #define PG8_SCHED __builtin_amdgcn_sched_barrier(0)
; template <class EpiT, class Sched>
; __device__ __forceinline__ void gemm_phase(LAS unsigned char* lds, const Gemm g, const Sched& S, const EpiT& E, int wv) {
;     ...
;             const bool last = (t == nt - 2);
;             const char* a1 = cA + (size_t)(t + 1) * kstep;
;             const char* a2 = last ? nA : cA + (size_t)(t + 2) * kstep; const char* b2 = last ? nB : cB + (size_t)(t + 2) * kstep;
;             const char* a3 = a2 + kstep; const char* b3 = b2 + kstep;
;             PG8_LDB(B0, 0, 0); PG8_LDB(B1, 0, 1); PG8_SCHED; PG8_LDA(At, 0, 0); PG8_STAGE(PG8_SA(1, 1), a1 + hstepA, voffA);
;             PG8_WAIT_V(8); PG8_WAIT_L(0); PG8_BAR; PG8_MMA(0, 0, At, B0); PG8_MMA(0, 1, At, B1); PG8_BAR; PG8_SCHED;
;             PG8_LDA(At, 0, 1); PG8_STAGE(PG8_SB(0, 0), b2, voffB); PG8_STAGE(PG8_SB(0, 1), b2 + hstepB, voffB); PG8_STAGE(PG8_SA(0, 0), a2, voffA);
;             PG8_WAIT_V(8); PG8_WAIT_L(0); PG8_BAR; PG8_MMA(1, 0, At, B0); PG8_MMA(1, 1, At, B1); PG8_BAR; PG8_SCHED;
.LBB0_1042:
	s_add_u32 s24, s22, 0xfff80080
	s_addc_u32 s25, s23, -1
	s_add_i32 s56, 0, 0x10000
	s_cmp_eq_u32 s55, 4
	s_cselect_b32 s27, s1, s25
	s_cselect_b32 s26, s15, s24
	s_cselect_b32 s25, s13, s54
	s_cselect_b32 s24, s33, s53
	s_add_i32 s58, 0, 0x14000
	ds_read_b128 v[128:131], v250
	ds_read_b128 v[132:135], v250 offset:1024
	ds_read_b128 v[136:139], v250 offset:2048
	ds_read_b128 v[140:143], v250 offset:3072
	ds_read_b128 v[144:147], v251
	ds_read_b128 v[148:151], v251 offset:1024
	ds_read_b128 v[152:155], v251 offset:2048
	ds_read_b128 v[166:169], v251 offset:3072
	s_add_i32 m0, s21, 0xc000
	ds_read_b128 v[170:173], v213
	ds_read_b128 v[174:177], v213 offset:1024
	ds_read_b128 v[178:181], v213 offset:2048
	ds_read_b128 v[182:185], v213 offset:3072
	ds_read_b128 v[186:189], v213 offset:4096
	ds_read_b128 v[204:207], v213 offset:5120
	ds_read_b128 v[208:211], v213 offset:6144
	ds_read_b128 v[214:217], v213 offset:7168
	global_load_lds_dwordx4 v162, s[22:23]
	s_add_i32 m0, s21, 0xe000
	s_nop 0
	global_load_lds_dwordx4 v164, s[22:23]
	s_waitcnt vmcnt(8)
	s_waitcnt lgkmcnt(0)
	s_barrier
	s_setprio 1
	v_mfma_f32_16x16x32_bf16 v[124:127], v[128:131], v[170:173], v[124:127]
	v_mfma_f32_16x16x32_bf16 v[120:123], v[136:139], v[170:173], v[120:123]
	v_mfma_f32_16x16x32_bf16 v[116:119], v[128:131], v[178:181], v[116:119]
	v_mfma_f32_16x16x32_bf16 v[112:115], v[136:139], v[178:181], v[112:115]
	v_mfma_f32_16x16x32_bf16 v[108:111], v[128:131], v[186:189], v[108:111]
	v_mfma_f32_16x16x32_bf16 v[104:107], v[136:139], v[186:189], v[104:107]
	v_mfma_f32_16x16x32_bf16 v[100:103], v[128:131], v[208:211], v[100:103]
	v_mfma_f32_16x16x32_bf16 v[96:99], v[136:139], v[208:211], v[96:99]
	v_mfma_f32_16x16x32_bf16 v[124:127], v[132:135], v[174:177], v[124:127]
	v_mfma_f32_16x16x32_bf16 v[120:123], v[140:143], v[174:177], v[120:123]
	v_mfma_f32_16x16x32_bf16 v[116:119], v[132:135], v[182:185], v[116:119]
	v_mfma_f32_16x16x32_bf16 v[112:115], v[140:143], v[182:185], v[112:115]
	v_mfma_f32_16x16x32_bf16 v[108:111], v[132:135], v[204:207], v[108:111]
	v_mfma_f32_16x16x32_bf16 v[104:107], v[140:143], v[204:207], v[104:107]
	v_mfma_f32_16x16x32_bf16 v[100:103], v[132:135], v[214:217], v[100:103]
	v_mfma_f32_16x16x32_bf16 v[96:99], v[140:143], v[214:217], v[96:99]
	s_setprio 0
	s_setprio 1
	v_mfma_f32_16x16x32_bf16 v[60:63], v[144:147], v[170:173], v[60:63]
	v_mfma_f32_16x16x32_bf16 v[56:59], v[152:155], v[170:173], v[56:59]
	v_mfma_f32_16x16x32_bf16 v[52:55], v[144:147], v[178:181], v[52:55]
	v_mfma_f32_16x16x32_bf16 v[48:51], v[152:155], v[178:181], v[48:51]
	v_mfma_f32_16x16x32_bf16 v[44:47], v[144:147], v[186:189], v[44:47]
	v_mfma_f32_16x16x32_bf16 v[40:43], v[152:155], v[186:189], v[40:43]
	v_mfma_f32_16x16x32_bf16 v[36:39], v[144:147], v[208:211], v[36:39]
	v_mfma_f32_16x16x32_bf16 v[32:35], v[152:155], v[208:211], v[32:35]
	v_mfma_f32_16x16x32_bf16 v[60:63], v[148:151], v[174:177], v[60:63]
	v_mfma_f32_16x16x32_bf16 v[56:59], v[166:169], v[174:177], v[56:59]
	v_mfma_f32_16x16x32_bf16 v[52:55], v[148:151], v[182:185], v[52:55]
	v_mfma_f32_16x16x32_bf16 v[48:51], v[166:169], v[182:185], v[48:51]
	v_mfma_f32_16x16x32_bf16 v[44:47], v[148:151], v[204:207], v[44:47]
	v_mfma_f32_16x16x32_bf16 v[40:43], v[166:169], v[204:207], v[40:43]
	v_mfma_f32_16x16x32_bf16 v[36:39], v[148:151], v[214:217], v[36:39]
	v_mfma_f32_16x16x32_bf16 v[32:35], v[166:169], v[214:217], v[32:35]
	s_setprio 0
	s_barrier
	s_add_i32 s56, s56, s39
	s_add_u32 s62, s24, s92
	s_addc_u32 s63, s25, s93
	s_mov_b32 m0, s56
	ds_read_b128 v[170:173], v213 offset:16384
	ds_read_b128 v[174:177], v213 offset:17408
	ds_read_b128 v[178:181], v213 offset:18432
	ds_read_b128 v[182:185], v213 offset:19456
	ds_read_b128 v[186:189], v213 offset:20480
	ds_read_b128 v[204:207], v213 offset:21504
	ds_read_b128 v[208:211], v213 offset:22528
	ds_read_b128 v[214:217], v213 offset:23552
	global_load_lds_dwordx4 v192, s[24:25]
	s_add_i32 m0, s56, 0x2000
	s_add_u32 s56, s24, 0x20000
	s_addc_u32 s57, s25, 0
	s_add_i32 s58, s58, s39
	global_load_lds_dwordx4 v156, s[24:25]
	s_mov_b32 m0, s58
	s_nop 0
	global_load_lds_dwordx4 v192, s[56:57]
	s_add_i32 m0, s58, 0x2000
	s_nop 0
	global_load_lds_dwordx4 v156, s[56:57]
	s_add_u32 s64, s26, s92
	s_addc_u32 s65, s27, s93
	s_mov_b32 m0, s21
	s_nop 0
	global_load_lds_dwordx4 v160, s[26:27]
	s_mov_b32 m0, s45
	s_nop 0
	global_load_lds_dwordx4 v158, s[26:27]
	s_waitcnt vmcnt(8)
	s_waitcnt lgkmcnt(0)
	s_barrier
	s_setprio 1
	v_mfma_f32_16x16x32_bf16 v[92:95], v[128:131], v[170:173], v[92:95]
	v_mfma_f32_16x16x32_bf16 v[88:91], v[136:139], v[170:173], v[88:91]
	v_mfma_f32_16x16x32_bf16 v[84:87], v[128:131], v[178:181], v[84:87]
	v_mfma_f32_16x16x32_bf16 v[80:83], v[136:139], v[178:181], v[80:83]
	v_mfma_f32_16x16x32_bf16 v[76:79], v[128:131], v[186:189], v[76:79]
	v_mfma_f32_16x16x32_bf16 v[72:75], v[136:139], v[186:189], v[72:75]
	v_mfma_f32_16x16x32_bf16 v[68:71], v[128:131], v[208:211], v[68:71]
	v_mfma_f32_16x16x32_bf16 v[64:67], v[136:139], v[208:211], v[64:67]
	v_mfma_f32_16x16x32_bf16 v[92:95], v[132:135], v[174:177], v[92:95]
	v_mfma_f32_16x16x32_bf16 v[88:91], v[140:143], v[174:177], v[88:91]
	v_mfma_f32_16x16x32_bf16 v[84:87], v[132:135], v[182:185], v[84:87]
	v_mfma_f32_16x16x32_bf16 v[80:83], v[140:143], v[182:185], v[80:83]
	v_mfma_f32_16x16x32_bf16 v[76:79], v[132:135], v[204:207], v[76:79]
	v_mfma_f32_16x16x32_bf16 v[72:75], v[140:143], v[204:207], v[72:75]
	v_mfma_f32_16x16x32_bf16 v[68:71], v[132:135], v[214:217], v[68:71]
	v_mfma_f32_16x16x32_bf16 v[64:67], v[140:143], v[214:217], v[64:67]
	s_setprio 0
	s_setprio 1
	v_mfma_f32_16x16x32_bf16 v[28:31], v[144:147], v[170:173], v[28:31]
	v_mfma_f32_16x16x32_bf16 v[24:27], v[152:155], v[170:173], v[24:27]
	v_mfma_f32_16x16x32_bf16 v[20:23], v[144:147], v[178:181], v[20:23]
	v_mfma_f32_16x16x32_bf16 v[16:19], v[152:155], v[178:181], v[16:19]
	v_mfma_f32_16x16x32_bf16 v[12:15], v[144:147], v[186:189], v[12:15]
	v_mfma_f32_16x16x32_bf16 v[8:11], v[152:155], v[186:189], v[8:11]
	v_mfma_f32_16x16x32_bf16 v[4:7], v[144:147], v[208:211], v[4:7]
	v_mfma_f32_16x16x32_bf16 v[0:3], v[152:155], v[208:211], v[0:3]
	v_mfma_f32_16x16x32_bf16 v[28:31], v[148:151], v[174:177], v[28:31]
	v_mfma_f32_16x16x32_bf16 v[24:27], v[166:169], v[174:177], v[24:27]
	v_mfma_f32_16x16x32_bf16 v[20:23], v[148:151], v[182:185], v[20:23]
	v_mfma_f32_16x16x32_bf16 v[16:19], v[166:169], v[182:185], v[16:19]
	v_mfma_f32_16x16x32_bf16 v[12:15], v[148:151], v[204:207], v[12:15]
	v_mfma_f32_16x16x32_bf16 v[8:11], v[166:169], v[204:207], v[8:11]
	v_mfma_f32_16x16x32_bf16 v[4:7], v[148:151], v[214:217], v[4:7]
	v_mfma_f32_16x16x32_bf16 v[0:3], v[166:169], v[214:217], v[0:3]
	s_setprio 0
	s_barrier
; #define PG8_STAGE(bufoff, gbase, voff) do { _Pragma("unroll") for (int _i = 0; _i < 2; ++_i) \
;         __builtin_amdgcn_global_load_lds((const unsigned*)((const char*)(gbase) + (voff)[_i]), (LAS unsigned*)(lds + (bufoff) + ldsw + _i * 8192), 16, 0, 0); } while (0)
; #define PG8_LDA(dst, b, h) do { _Pragma("unroll") for (int m = 0; m < 4; ++m) _Pragma("unroll") for (int k = 0; k < 2; ++k) dst[m][k] = *(const LAS bf16x8*)(lds + PG8_SA(b, h) + aoff + m * 2048 + k * 1024); } while (0)
; #define PG8_LDB(dst, b, h) do { _Pragma("unroll") for (int n = 0; n < 2; ++n) _Pragma("unroll") for (int k = 0; k < 2; ++k) dst[n][k] = *(const LAS bf16x8*)(lds + PG8_SB(b, h) + boff + n * 2048 + k * 1024); } while (0)
; #define PG8_MMA(ai, bj, At, Bt) do { __builtin_amdgcn_s_setprio(1); _Pragma("unroll") for (int m = 0; m < 4; ++m) _Pragma("unroll") for (int n = 0; n < 2; ++n) _Pragma("unroll") for (int k = 0; k < 2; ++k) \
;         acc[ai][bj][m][n] = __builtin_amdgcn_mfma_f32_16x16x32_bf16(Bt[n][k], At[m][k], acc[ai][bj][m][n], 0, 0, 0); __builtin_amdgcn_s_setprio(0); } while (0)
; #define PG8_WAIT_V(n) asm volatile("s_waitcnt vmcnt(" #n ")" ::: "memory")
; template <class EpiT, class Sched>
; __device__ __forceinline__ void gemm_phase(LAS unsigned char* lds, const Gemm g, const Sched& S, const EpiT& E, int wv) {
;     ...
;             PG8_LDB(B0, 0, 0); PG8_LDB(B1, 0, 1); PG8_SCHED; PG8_LDA(At, 0, 0); PG8_STAGE(PG8_SA(1, 1), a1 + hstepA, voffA);
;             PG8_WAIT_V(8); PG8_WAIT_L(0); PG8_BAR; PG8_MMA(0, 0, At, B0); PG8_MMA(0, 1, At, B1); PG8_BAR; PG8_SCHED;
;             PG8_LDA(At, 0, 1); PG8_STAGE(PG8_SB(0, 0), b2, voffB); PG8_STAGE(PG8_SB(0, 1), b2 + hstepB, voffB); PG8_STAGE(PG8_SA(0, 0), a2, voffA);
;             PG8_WAIT_V(8); PG8_WAIT_L(0); PG8_BAR; PG8_MMA(1, 0, At, B0); PG8_MMA(1, 1, At, B1); PG8_BAR; PG8_SCHED;
;             PG8_LDB(B0, 1, 0); PG8_LDB(B1, 1, 1); PG8_SCHED; PG8_LDA(At, 1, 0); PG8_STAGE(PG8_SA(0, 1), a2 + hstepA, voffA);
;             PG8_WAIT_V(8); PG8_WAIT_L(0); PG8_BAR; PG8_MMA(0, 0, At, B0); PG8_MMA(0, 1, At, B1); PG8_BAR; PG8_SCHED;
;             PG8_LDA(At, 1, 1); PG8_STAGE(PG8_SB(1, 0), b3, voffB); PG8_STAGE(PG8_SB(1, 1), b3 + hstepB, voffB); PG8_STAGE(PG8_SA(1, 0), a3, voffA);
;             PG8_WAIT_V(8); PG8_WAIT_L(0); PG8_BAR; PG8_MMA(1, 0, At, B0); PG8_MMA(1, 1, At, B1); PG8_BAR; PG8_SCHED;
;         }
;         if (wr == 0) PG8_BAR;
	s_add_i32 s56, 0, 0x18000
	s_add_i32 s57, 0, 0x1c000
	ds_read_b128 v[128:131], v252
	ds_read_b128 v[132:135], v252 offset:1024
	ds_read_b128 v[136:139], v252 offset:2048
	ds_read_b128 v[140:143], v252 offset:3072
	ds_read_b128 v[144:147], v253
	ds_read_b128 v[148:151], v253 offset:1024
	ds_read_b128 v[152:155], v253 offset:2048
	ds_read_b128 v[166:169], v253 offset:3072
	s_add_u32 s26, s26, 0x80000
	s_addc_u32 s27, s27, 0
	s_mov_b32 m0, s46
	ds_read_b128 v[170:173], v213 offset:32768
	ds_read_b128 v[174:177], v213 offset:33792
	ds_read_b128 v[178:181], v213 offset:34816
	ds_read_b128 v[182:185], v213 offset:35840
	ds_read_b128 v[186:189], v213 offset:36864
	ds_read_b128 v[204:207], v213 offset:37888
	ds_read_b128 v[208:211], v213 offset:38912
	ds_read_b128 v[214:217], v213 offset:39936
	global_load_lds_dwordx4 v160, s[26:27]
	s_mov_b32 m0, s47
	s_nop 0
	global_load_lds_dwordx4 v158, s[26:27]
	s_waitcnt vmcnt(8)
	s_waitcnt lgkmcnt(0)
	s_barrier
	s_setprio 1
	v_mfma_f32_16x16x32_bf16 v[124:127], v[128:131], v[170:173], v[124:127]
	v_mfma_f32_16x16x32_bf16 v[120:123], v[136:139], v[170:173], v[120:123]
	v_mfma_f32_16x16x32_bf16 v[116:119], v[128:131], v[178:181], v[116:119]
	v_mfma_f32_16x16x32_bf16 v[112:115], v[136:139], v[178:181], v[112:115]
	v_mfma_f32_16x16x32_bf16 v[108:111], v[128:131], v[186:189], v[108:111]
	v_mfma_f32_16x16x32_bf16 v[104:107], v[136:139], v[186:189], v[104:107]
	v_mfma_f32_16x16x32_bf16 v[100:103], v[128:131], v[208:211], v[100:103]
	v_mfma_f32_16x16x32_bf16 v[96:99], v[136:139], v[208:211], v[96:99]
	v_mfma_f32_16x16x32_bf16 v[124:127], v[132:135], v[174:177], v[124:127]
	v_mfma_f32_16x16x32_bf16 v[120:123], v[140:143], v[174:177], v[120:123]
	v_mfma_f32_16x16x32_bf16 v[116:119], v[132:135], v[182:185], v[116:119]
	v_mfma_f32_16x16x32_bf16 v[112:115], v[140:143], v[182:185], v[112:115]
	v_mfma_f32_16x16x32_bf16 v[108:111], v[132:135], v[204:207], v[108:111]
	v_mfma_f32_16x16x32_bf16 v[104:107], v[140:143], v[204:207], v[104:107]
	v_mfma_f32_16x16x32_bf16 v[100:103], v[132:135], v[214:217], v[100:103]
	v_mfma_f32_16x16x32_bf16 v[96:99], v[140:143], v[214:217], v[96:99]
	s_setprio 0
	s_setprio 1
	v_mfma_f32_16x16x32_bf16 v[60:63], v[144:147], v[170:173], v[60:63]
	v_mfma_f32_16x16x32_bf16 v[56:59], v[152:155], v[170:173], v[56:59]
	v_mfma_f32_16x16x32_bf16 v[52:55], v[144:147], v[178:181], v[52:55]
	v_mfma_f32_16x16x32_bf16 v[48:51], v[152:155], v[178:181], v[48:51]
	v_mfma_f32_16x16x32_bf16 v[44:47], v[144:147], v[186:189], v[44:47]
	v_mfma_f32_16x16x32_bf16 v[40:43], v[152:155], v[186:189], v[40:43]
	v_mfma_f32_16x16x32_bf16 v[36:39], v[144:147], v[208:211], v[36:39]
	v_mfma_f32_16x16x32_bf16 v[32:35], v[152:155], v[208:211], v[32:35]
	v_mfma_f32_16x16x32_bf16 v[60:63], v[148:151], v[174:177], v[60:63]
	v_mfma_f32_16x16x32_bf16 v[56:59], v[166:169], v[174:177], v[56:59]
	v_mfma_f32_16x16x32_bf16 v[52:55], v[148:151], v[182:185], v[52:55]
	v_mfma_f32_16x16x32_bf16 v[48:51], v[166:169], v[182:185], v[48:51]
	v_mfma_f32_16x16x32_bf16 v[44:47], v[148:151], v[204:207], v[44:47]
	v_mfma_f32_16x16x32_bf16 v[40:43], v[166:169], v[204:207], v[40:43]
	v_mfma_f32_16x16x32_bf16 v[36:39], v[148:151], v[214:217], v[36:39]
	v_mfma_f32_16x16x32_bf16 v[32:35], v[166:169], v[214:217], v[32:35]
	s_setprio 0
	s_barrier
	s_add_i32 s26, s56, s39
	s_mov_b32 m0, s26
	ds_read_b128 v[170:173], v213 offset:49152
	ds_read_b128 v[174:177], v213 offset:50176
	ds_read_b128 v[178:181], v213 offset:51200
	ds_read_b128 v[182:185], v213 offset:52224
	ds_read_b128 v[186:189], v213 offset:53248
	ds_read_b128 v[204:207], v213 offset:54272
	ds_read_b128 v[208:211], v213 offset:55296
	ds_read_b128 v[214:217], v213 offset:56320
	global_load_lds_dwordx4 v192, s[62:63]
	s_add_i32 m0, s26, 0x2000
	s_add_u32 s24, s24, 0x20080
	s_addc_u32 s25, s25, 0
	s_add_i32 s26, s57, s39
	global_load_lds_dwordx4 v156, s[62:63]
	s_mov_b32 m0, s26
	s_nop 0
	global_load_lds_dwordx4 v192, s[24:25]
	s_add_i32 m0, s26, 0x2000
	s_nop 0
	global_load_lds_dwordx4 v156, s[24:25]
	s_mov_b32 m0, s48
	s_nop 0
	global_load_lds_dwordx4 v160, s[64:65]
	s_mov_b32 m0, s49
	s_nop 0
	global_load_lds_dwordx4 v158, s[64:65]
	s_waitcnt vmcnt(8)
	s_waitcnt lgkmcnt(0)
	s_barrier
	s_setprio 1
	v_mfma_f32_16x16x32_bf16 v[92:95], v[128:131], v[170:173], v[92:95]
	v_mfma_f32_16x16x32_bf16 v[88:91], v[136:139], v[170:173], v[88:91]
	v_mfma_f32_16x16x32_bf16 v[84:87], v[128:131], v[178:181], v[84:87]
	v_mfma_f32_16x16x32_bf16 v[80:83], v[136:139], v[178:181], v[80:83]
	v_mfma_f32_16x16x32_bf16 v[76:79], v[128:131], v[186:189], v[76:79]
	v_mfma_f32_16x16x32_bf16 v[72:75], v[136:139], v[186:189], v[72:75]
	v_mfma_f32_16x16x32_bf16 v[68:71], v[128:131], v[208:211], v[68:71]
	v_mfma_f32_16x16x32_bf16 v[64:67], v[136:139], v[208:211], v[64:67]
	v_mfma_f32_16x16x32_bf16 v[92:95], v[132:135], v[174:177], v[92:95]
	v_mfma_f32_16x16x32_bf16 v[88:91], v[140:143], v[174:177], v[88:91]
	v_mfma_f32_16x16x32_bf16 v[84:87], v[132:135], v[182:185], v[84:87]
	v_mfma_f32_16x16x32_bf16 v[80:83], v[140:143], v[182:185], v[80:83]
	v_mfma_f32_16x16x32_bf16 v[76:79], v[132:135], v[204:207], v[76:79]
	v_mfma_f32_16x16x32_bf16 v[72:75], v[140:143], v[204:207], v[72:75]
	v_mfma_f32_16x16x32_bf16 v[68:71], v[132:135], v[214:217], v[68:71]
	v_mfma_f32_16x16x32_bf16 v[64:67], v[140:143], v[214:217], v[64:67]
	s_setprio 0
	s_setprio 1
	v_mfma_f32_16x16x32_bf16 v[28:31], v[144:147], v[170:173], v[28:31]
	v_mfma_f32_16x16x32_bf16 v[24:27], v[152:155], v[170:173], v[24:27]
	v_mfma_f32_16x16x32_bf16 v[20:23], v[144:147], v[178:181], v[20:23]
	v_mfma_f32_16x16x32_bf16 v[16:19], v[152:155], v[178:181], v[16:19]
	v_mfma_f32_16x16x32_bf16 v[12:15], v[144:147], v[186:189], v[12:15]
	v_mfma_f32_16x16x32_bf16 v[8:11], v[152:155], v[186:189], v[8:11]
	v_mfma_f32_16x16x32_bf16 v[4:7], v[144:147], v[208:211], v[4:7]
	v_mfma_f32_16x16x32_bf16 v[0:3], v[152:155], v[208:211], v[0:3]
	v_mfma_f32_16x16x32_bf16 v[28:31], v[148:151], v[174:177], v[28:31]
	v_mfma_f32_16x16x32_bf16 v[24:27], v[166:169], v[174:177], v[24:27]
	v_mfma_f32_16x16x32_bf16 v[20:23], v[148:151], v[182:185], v[20:23]
	v_mfma_f32_16x16x32_bf16 v[16:19], v[166:169], v[182:185], v[16:19]
	v_mfma_f32_16x16x32_bf16 v[12:15], v[148:151], v[204:207], v[12:15]
	v_mfma_f32_16x16x32_bf16 v[8:11], v[166:169], v[204:207], v[8:11]
	v_mfma_f32_16x16x32_bf16 v[4:7], v[148:151], v[214:217], v[4:7]
	v_mfma_f32_16x16x32_bf16 v[0:3], v[166:169], v[214:217], v[0:3]
	s_setprio 0
	s_barrier
	s_add_i32 s55, s55, 2
	s_add_u32 s22, s22, 0x100
	s_addc_u32 s23, s23, 0
	s_add_u32 s53, s53, 0x100
	s_addc_u32 s54, s54, 0
	s_cmp_gt_u32 s55, 5
	s_cbranch_scc0 .LBB0_1042
	s_and_b64 vcc, exec, s[10:11]
	s_cbranch_vccz .LBB0_1045
	s_barrier

; #define PG8_STAGE(bufoff, gbase, voff) do { _Pragma("unroll") for (int _i = 0; _i < 2; ++_i) \
;         __builtin_amdgcn_global_load_lds((const unsigned*)((const char*)(gbase) + (voff)[_i]), (LAS unsigned*)(lds + (bufoff) + ldsw + _i * 8192), 16, 0, 0); } while (0)
; #define PG8_LDA(dst, b, h) do { _Pragma("unroll") for (int m = 0; m < 4; ++m) _Pragma("unroll") for (int k = 0; k < 2; ++k) dst[m][k] = *(const LAS bf16x8*)(lds + PG8_SA(b, h) + aoff + m * 2048 + k * 1024); } while (0)
; #define PG8_LDB(dst, b, h) do { _Pragma("unroll") for (int n = 0; n < 2; ++n) _Pragma("unroll") for (int k = 0; k < 2; ++k) dst[n][k] = *(const LAS bf16x8*)(lds + PG8_SB(b, h) + boff + n * 2048 + k * 1024); } while (0)
; #define PG8_MMA(ai, bj, At, Bt) do { __builtin_amdgcn_s_setprio(1); _Pragma("unroll") for (int m = 0; m < 4; ++m) _Pragma("unroll") for (int n = 0; n < 2; ++n) _Pragma("unroll") for (int k = 0; k < 2; ++k) \
;         acc[ai][bj][m][n] = __builtin_amdgcn_mfma_f32_16x16x32_bf16(Bt[n][k], At[m][k], acc[ai][bj][m][n], 0, 0, 0); __builtin_amdgcn_s_setprio(0); } while (0)
; #define PG8_WAIT_V(n) asm volatile("s_waitcnt vmcnt(" #n ")" ::: "memory")
; template <class EpiT, class Sched>
; __device__ __forceinline__ void gemm_phase(LAS unsigned char* lds, const Gemm g, const Sched& S, const EpiT& E, int wv) {
;     ...
;         const char* nA = has_next ? (const char*)g.A + (size_t)nxt.pm * tstepA + (size_t)(nxt.pn >> g.zshift) * g.zA : cA; const char* nB = has_next ? (const char*)g.Bt + (size_t)nxt.pn * tstepB : cB;
;         for (int t = 0; t < nt; t += 2) {
;             const bool last = (t == nt - 2);
;             const char* a1 = cA + (size_t)(t + 1) * kstep;
;             const char* a2 = last ? nA : cA + (size_t)(t + 2) * kstep; const char* b2 = last ? nB : cB + (size_t)(t + 2) * kstep;
;             const char* a3 = a2 + kstep; const char* b3 = b2 + kstep;
;             PG8_LDB(B0, 0, 0); PG8_LDB(B1, 0, 1); PG8_SCHED; PG8_LDA(At, 0, 0); PG8_STAGE(PG8_SA(1, 1), a1 + hstepA, voffA);
;             PG8_WAIT_V(8); PG8_WAIT_L(0); PG8_BAR; PG8_MMA(0, 0, At, B0); PG8_MMA(0, 1, At, B1); PG8_BAR; PG8_SCHED;
;             PG8_LDA(At, 0, 1); PG8_STAGE(PG8_SB(0, 0), b2, voffB); PG8_STAGE(PG8_SB(0, 1), b2 + hstepB, voffB); PG8_STAGE(PG8_SA(0, 0), a2, voffA);
;             PG8_WAIT_V(8); PG8_WAIT_L(0); PG8_BAR; PG8_MMA(1, 0, At, B0); PG8_MMA(1, 1, At, B1); PG8_BAR; PG8_SCHED;
.LBB0_1154:
	s_add_u32 s38, s4, 0xfffc0080
	s_addc_u32 s39, s5, -1
	s_add_i32 s90, 0, 0x10000
	s_cmp_eq_u32 s89, 12
	s_cselect_b32 s41, s1, s39
	s_cselect_b32 s40, s25, s38
	s_cselect_b32 s39, s23, s65
	s_cselect_b32 s38, s33, s64
	s_add_i32 vcc_lo, 0, 0x14000
	ds_read_b128 v[120:123], v250
	ds_read_b128 v[124:127], v250 offset:1024
	ds_read_b128 v[136:139], v250 offset:2048
	ds_read_b128 v[140:143], v250 offset:3072
	ds_read_b128 v[144:147], v251
	ds_read_b128 v[148:151], v251 offset:1024
	ds_read_b128 v[152:155], v251 offset:2048
	ds_read_b128 v[156:159], v251 offset:3072
	s_add_i32 m0, s27, 0xc000
	ds_read_b128 v[160:163], v241
	ds_read_b128 v[164:167], v241 offset:1024
	ds_read_b128 v[178:181], v241 offset:2048
	ds_read_b128 v[182:185], v241 offset:3072
	ds_read_b128 v[186:189], v241 offset:4096
	ds_read_b128 v[204:207], v241 offset:5120
	ds_read_b128 v[208:211], v241 offset:6144
	ds_read_b128 v[212:215], v241 offset:7168
	global_load_lds_dwordx4 v174, s[4:5]
	s_add_i32 m0, s27, 0xe000
	s_nop 0
	global_load_lds_dwordx4 v176, s[4:5]
	s_waitcnt vmcnt(8)
	s_waitcnt lgkmcnt(0)
	s_barrier
	s_setprio 1
	v_mfma_f32_16x16x32_bf16 v[132:135], v[120:123], v[160:163], v[132:135]
	v_mfma_f32_16x16x32_bf16 v[128:131], v[136:139], v[160:163], v[128:131]
	v_mfma_f32_16x16x32_bf16 v[116:119], v[120:123], v[178:181], v[116:119]
	v_mfma_f32_16x16x32_bf16 v[112:115], v[136:139], v[178:181], v[112:115]
	v_mfma_f32_16x16x32_bf16 v[108:111], v[120:123], v[186:189], v[108:111]
	v_mfma_f32_16x16x32_bf16 v[104:107], v[136:139], v[186:189], v[104:107]
	v_mfma_f32_16x16x32_bf16 v[100:103], v[120:123], v[208:211], v[100:103]
	v_mfma_f32_16x16x32_bf16 v[96:99], v[136:139], v[208:211], v[96:99]
	v_mfma_f32_16x16x32_bf16 v[132:135], v[124:127], v[164:167], v[132:135]
	v_mfma_f32_16x16x32_bf16 v[128:131], v[140:143], v[164:167], v[128:131]
	v_mfma_f32_16x16x32_bf16 v[116:119], v[124:127], v[182:185], v[116:119]
	v_mfma_f32_16x16x32_bf16 v[112:115], v[140:143], v[182:185], v[112:115]
	v_mfma_f32_16x16x32_bf16 v[108:111], v[124:127], v[204:207], v[108:111]
	v_mfma_f32_16x16x32_bf16 v[104:107], v[140:143], v[204:207], v[104:107]
	v_mfma_f32_16x16x32_bf16 v[100:103], v[124:127], v[212:215], v[100:103]
	v_mfma_f32_16x16x32_bf16 v[96:99], v[140:143], v[212:215], v[96:99]
	s_setprio 0
	s_setprio 1
	v_mfma_f32_16x16x32_bf16 v[60:63], v[144:147], v[160:163], v[60:63]
	v_mfma_f32_16x16x32_bf16 v[56:59], v[152:155], v[160:163], v[56:59]
	v_mfma_f32_16x16x32_bf16 v[52:55], v[144:147], v[178:181], v[52:55]
	v_mfma_f32_16x16x32_bf16 v[48:51], v[152:155], v[178:181], v[48:51]
	v_mfma_f32_16x16x32_bf16 v[44:47], v[144:147], v[186:189], v[44:47]
	v_mfma_f32_16x16x32_bf16 v[40:43], v[152:155], v[186:189], v[40:43]
	v_mfma_f32_16x16x32_bf16 v[36:39], v[144:147], v[208:211], v[36:39]
	v_mfma_f32_16x16x32_bf16 v[32:35], v[152:155], v[208:211], v[32:35]
	v_mfma_f32_16x16x32_bf16 v[60:63], v[148:151], v[164:167], v[60:63]
	v_mfma_f32_16x16x32_bf16 v[56:59], v[156:159], v[164:167], v[56:59]
	v_mfma_f32_16x16x32_bf16 v[52:55], v[148:151], v[182:185], v[52:55]
	v_mfma_f32_16x16x32_bf16 v[48:51], v[156:159], v[182:185], v[48:51]
	v_mfma_f32_16x16x32_bf16 v[44:47], v[148:151], v[204:207], v[44:47]
	v_mfma_f32_16x16x32_bf16 v[40:43], v[156:159], v[204:207], v[40:43]
	v_mfma_f32_16x16x32_bf16 v[36:39], v[148:151], v[212:215], v[36:39]
	v_mfma_f32_16x16x32_bf16 v[32:35], v[156:159], v[212:215], v[32:35]
	s_setprio 0
	s_barrier
	s_add_i32 s90, s90, s48
	s_add_u32 s36, s38, s92
	s_addc_u32 s37, s39, s93
	s_mov_b32 m0, s90
	ds_read_b128 v[160:163], v241 offset:16384
	ds_read_b128 v[164:167], v241 offset:17408
	ds_read_b128 v[178:181], v241 offset:18432
	ds_read_b128 v[182:185], v241 offset:19456
	ds_read_b128 v[186:189], v241 offset:20480
	ds_read_b128 v[204:207], v241 offset:21504
	ds_read_b128 v[208:211], v241 offset:22528
	ds_read_b128 v[212:215], v241 offset:23552
	global_load_lds_dwordx4 v192, s[38:39]
	s_add_i32 m0, s90, 0x2000
	s_add_u32 s90, s38, 0x100000
	s_addc_u32 s91, s39, 0
	s_add_i32 vcc_lo, vcc_lo, s48
	global_load_lds_dwordx4 v172, s[38:39]
	s_mov_b32 m0, vcc_lo
	s_nop 0
	global_load_lds_dwordx4 v192, s[90:91]
	s_add_i32 m0, vcc_lo, 0x2000
	s_nop 0
	global_load_lds_dwordx4 v172, s[90:91]
	s_add_u32 s98, s40, s92
	s_addc_u32 s99, s41, s93
	s_mov_b32 m0, s27
	s_nop 0
	global_load_lds_dwordx4 v168, s[40:41]
	s_mov_b32 m0, s53
	s_nop 0
	global_load_lds_dwordx4 v170, s[40:41]
	s_waitcnt vmcnt(8)
	s_waitcnt lgkmcnt(0)
	s_barrier
	s_setprio 1
	v_mfma_f32_16x16x32_bf16 v[92:95], v[120:123], v[160:163], v[92:95]
	v_mfma_f32_16x16x32_bf16 v[88:91], v[136:139], v[160:163], v[88:91]
	v_mfma_f32_16x16x32_bf16 v[84:87], v[120:123], v[178:181], v[84:87]
	v_mfma_f32_16x16x32_bf16 v[80:83], v[136:139], v[178:181], v[80:83]
	v_mfma_f32_16x16x32_bf16 v[76:79], v[120:123], v[186:189], v[76:79]
	v_mfma_f32_16x16x32_bf16 v[72:75], v[136:139], v[186:189], v[72:75]
	v_mfma_f32_16x16x32_bf16 v[68:71], v[120:123], v[208:211], v[68:71]
	v_mfma_f32_16x16x32_bf16 v[64:67], v[136:139], v[208:211], v[64:67]
	v_mfma_f32_16x16x32_bf16 v[92:95], v[124:127], v[164:167], v[92:95]
	v_mfma_f32_16x16x32_bf16 v[88:91], v[140:143], v[164:167], v[88:91]
	v_mfma_f32_16x16x32_bf16 v[84:87], v[124:127], v[182:185], v[84:87]
	v_mfma_f32_16x16x32_bf16 v[80:83], v[140:143], v[182:185], v[80:83]
	v_mfma_f32_16x16x32_bf16 v[76:79], v[124:127], v[204:207], v[76:79]
	v_mfma_f32_16x16x32_bf16 v[72:75], v[140:143], v[204:207], v[72:75]
	v_mfma_f32_16x16x32_bf16 v[68:71], v[124:127], v[212:215], v[68:71]
	v_mfma_f32_16x16x32_bf16 v[64:67], v[140:143], v[212:215], v[64:67]
	s_setprio 0
	s_setprio 1
	v_mfma_f32_16x16x32_bf16 v[28:31], v[144:147], v[160:163], v[28:31]
	v_mfma_f32_16x16x32_bf16 v[24:27], v[152:155], v[160:163], v[24:27]
	v_mfma_f32_16x16x32_bf16 v[20:23], v[144:147], v[178:181], v[20:23]
	v_mfma_f32_16x16x32_bf16 v[16:19], v[152:155], v[178:181], v[16:19]
	v_mfma_f32_16x16x32_bf16 v[12:15], v[144:147], v[186:189], v[12:15]
	v_mfma_f32_16x16x32_bf16 v[8:11], v[152:155], v[186:189], v[8:11]
	v_mfma_f32_16x16x32_bf16 v[4:7], v[144:147], v[208:211], v[4:7]
	v_mfma_f32_16x16x32_bf16 v[0:3], v[152:155], v[208:211], v[0:3]
	v_mfma_f32_16x16x32_bf16 v[28:31], v[148:151], v[164:167], v[28:31]
	v_mfma_f32_16x16x32_bf16 v[24:27], v[156:159], v[164:167], v[24:27]
	v_mfma_f32_16x16x32_bf16 v[20:23], v[148:151], v[182:185], v[20:23]
	v_mfma_f32_16x16x32_bf16 v[16:19], v[156:159], v[182:185], v[16:19]
	v_mfma_f32_16x16x32_bf16 v[12:15], v[148:151], v[204:207], v[12:15]
	v_mfma_f32_16x16x32_bf16 v[8:11], v[156:159], v[204:207], v[8:11]
	v_mfma_f32_16x16x32_bf16 v[4:7], v[148:151], v[212:215], v[4:7]
	v_mfma_f32_16x16x32_bf16 v[0:3], v[156:159], v[212:215], v[0:3]
	s_setprio 0
	s_barrier
; #define PG8_STAGE(bufoff, gbase, voff) do { _Pragma("unroll") for (int _i = 0; _i < 2; ++_i) \
;         __builtin_amdgcn_global_load_lds((const unsigned*)((const char*)(gbase) + (voff)[_i]), (LAS unsigned*)(lds + (bufoff) + ldsw + _i * 8192), 16, 0, 0); } while (0)
; #define PG8_LDA(dst, b, h) do { _Pragma("unroll") for (int m = 0; m < 4; ++m) _Pragma("unroll") for (int k = 0; k < 2; ++k) dst[m][k] = *(const LAS bf16x8*)(lds + PG8_SA(b, h) + aoff + m * 2048 + k * 1024); } while (0)
; #define PG8_LDB(dst, b, h) do { _Pragma("unroll") for (int n = 0; n < 2; ++n) _Pragma("unroll") for (int k = 0; k < 2; ++k) dst[n][k] = *(const LAS bf16x8*)(lds + PG8_SB(b, h) + boff + n * 2048 + k * 1024); } while (0)
; #define PG8_MMA(ai, bj, At, Bt) do { __builtin_amdgcn_s_setprio(1); _Pragma("unroll") for (int m = 0; m < 4; ++m) _Pragma("unroll") for (int n = 0; n < 2; ++n) _Pragma("unroll") for (int k = 0; k < 2; ++k) \
;         acc[ai][bj][m][n] = __builtin_amdgcn_mfma_f32_16x16x32_bf16(Bt[n][k], At[m][k], acc[ai][bj][m][n], 0, 0, 0); __builtin_amdgcn_s_setprio(0); } while (0)
; #define PG8_WAIT_V(n) asm volatile("s_waitcnt vmcnt(" #n ")" ::: "memory")
; #define PG8_WAIT_L(n) asm volatile("s_waitcnt lgkmcnt(" #n ")" ::: "memory")
; #define PG8_BAR __builtin_amdgcn_s_barrier()
; #define PG8_SCHED __builtin_amdgcn_sched_barrier(0)
; template <class EpiT, class Sched>
; __device__ __forceinline__ void gemm_phase(LAS unsigned char* lds, const Gemm g, const Sched& S, const EpiT& E, int wv) {
;     ...
;             PG8_LDB(B0, 1, 0); PG8_LDB(B1, 1, 1); PG8_SCHED; PG8_LDA(At, 1, 0); PG8_STAGE(PG8_SA(0, 1), a2 + hstepA, voffA);
;             PG8_WAIT_V(8); PG8_WAIT_L(0); PG8_BAR; PG8_MMA(0, 0, At, B0); PG8_MMA(0, 1, At, B1); PG8_BAR; PG8_SCHED;
;             PG8_LDA(At, 1, 1); PG8_STAGE(PG8_SB(1, 0), b3, voffB); PG8_STAGE(PG8_SB(1, 1), b3 + hstepB, voffB); PG8_STAGE(PG8_SA(1, 0), a3, voffA);
;             PG8_WAIT_V(8); PG8_WAIT_L(0); PG8_BAR; PG8_MMA(1, 0, At, B0); PG8_MMA(1, 1, At, B1); PG8_BAR; PG8_SCHED;
;         }
;         if (wr == 0) PG8_BAR;
	s_add_i32 s90, 0, 0x18000
	s_add_i32 s91, 0, 0x1c000
	ds_read_b128 v[120:123], v252
	ds_read_b128 v[124:127], v252 offset:1024
	ds_read_b128 v[136:139], v252 offset:2048
	ds_read_b128 v[140:143], v252 offset:3072
	ds_read_b128 v[144:147], v253
	ds_read_b128 v[148:151], v253 offset:1024
	ds_read_b128 v[152:155], v253 offset:2048
	ds_read_b128 v[156:159], v253 offset:3072
	s_add_u32 s40, s40, 0x40000
	s_addc_u32 s41, s41, 0
	s_mov_b32 m0, s54
	ds_read_b128 v[160:163], v241 offset:32768
	ds_read_b128 v[164:167], v241 offset:33792
	ds_read_b128 v[178:181], v241 offset:34816
	ds_read_b128 v[182:185], v241 offset:35840
	ds_read_b128 v[186:189], v241 offset:36864
	ds_read_b128 v[204:207], v241 offset:37888
	ds_read_b128 v[208:211], v241 offset:38912
	ds_read_b128 v[212:215], v241 offset:39936
	global_load_lds_dwordx4 v168, s[40:41]
	s_mov_b32 m0, s55
	s_nop 0
	global_load_lds_dwordx4 v170, s[40:41]
	s_waitcnt vmcnt(8)
	s_waitcnt lgkmcnt(0)
	s_barrier
	s_setprio 1
	v_mfma_f32_16x16x32_bf16 v[132:135], v[120:123], v[160:163], v[132:135]
	v_mfma_f32_16x16x32_bf16 v[128:131], v[136:139], v[160:163], v[128:131]
	v_mfma_f32_16x16x32_bf16 v[116:119], v[120:123], v[178:181], v[116:119]
	v_mfma_f32_16x16x32_bf16 v[112:115], v[136:139], v[178:181], v[112:115]
	v_mfma_f32_16x16x32_bf16 v[108:111], v[120:123], v[186:189], v[108:111]
	v_mfma_f32_16x16x32_bf16 v[104:107], v[136:139], v[186:189], v[104:107]
	v_mfma_f32_16x16x32_bf16 v[100:103], v[120:123], v[208:211], v[100:103]
	v_mfma_f32_16x16x32_bf16 v[96:99], v[136:139], v[208:211], v[96:99]
	v_mfma_f32_16x16x32_bf16 v[132:135], v[124:127], v[164:167], v[132:135]
	v_mfma_f32_16x16x32_bf16 v[128:131], v[140:143], v[164:167], v[128:131]
	v_mfma_f32_16x16x32_bf16 v[116:119], v[124:127], v[182:185], v[116:119]
	v_mfma_f32_16x16x32_bf16 v[112:115], v[140:143], v[182:185], v[112:115]
	v_mfma_f32_16x16x32_bf16 v[108:111], v[124:127], v[204:207], v[108:111]
	v_mfma_f32_16x16x32_bf16 v[104:107], v[140:143], v[204:207], v[104:107]
	v_mfma_f32_16x16x32_bf16 v[100:103], v[124:127], v[212:215], v[100:103]
	v_mfma_f32_16x16x32_bf16 v[96:99], v[140:143], v[212:215], v[96:99]
	s_setprio 0
	s_setprio 1
	v_mfma_f32_16x16x32_bf16 v[60:63], v[144:147], v[160:163], v[60:63]
	v_mfma_f32_16x16x32_bf16 v[56:59], v[152:155], v[160:163], v[56:59]
	v_mfma_f32_16x16x32_bf16 v[52:55], v[144:147], v[178:181], v[52:55]
	v_mfma_f32_16x16x32_bf16 v[48:51], v[152:155], v[178:181], v[48:51]
	v_mfma_f32_16x16x32_bf16 v[44:47], v[144:147], v[186:189], v[44:47]
	v_mfma_f32_16x16x32_bf16 v[40:43], v[152:155], v[186:189], v[40:43]
	v_mfma_f32_16x16x32_bf16 v[36:39], v[144:147], v[208:211], v[36:39]
	v_mfma_f32_16x16x32_bf16 v[32:35], v[152:155], v[208:211], v[32:35]
	v_mfma_f32_16x16x32_bf16 v[60:63], v[148:151], v[164:167], v[60:63]
	v_mfma_f32_16x16x32_bf16 v[56:59], v[156:159], v[164:167], v[56:59]
	v_mfma_f32_16x16x32_bf16 v[52:55], v[148:151], v[182:185], v[52:55]
	v_mfma_f32_16x16x32_bf16 v[48:51], v[156:159], v[182:185], v[48:51]
	v_mfma_f32_16x16x32_bf16 v[44:47], v[148:151], v[204:207], v[44:47]
	v_mfma_f32_16x16x32_bf16 v[40:43], v[156:159], v[204:207], v[40:43]
	v_mfma_f32_16x16x32_bf16 v[36:39], v[148:151], v[212:215], v[36:39]
	v_mfma_f32_16x16x32_bf16 v[32:35], v[156:159], v[212:215], v[32:35]
	s_setprio 0
	s_barrier
	s_add_i32 s40, s90, s48
	s_mov_b32 m0, s40
	ds_read_b128 v[160:163], v241 offset:49152
	ds_read_b128 v[164:167], v241 offset:50176
	ds_read_b128 v[178:181], v241 offset:51200
	ds_read_b128 v[182:185], v241 offset:52224
	ds_read_b128 v[186:189], v241 offset:53248
	ds_read_b128 v[204:207], v241 offset:54272
	ds_read_b128 v[208:211], v241 offset:55296
	ds_read_b128 v[212:215], v241 offset:56320
	global_load_lds_dwordx4 v192, s[36:37]
	s_add_i32 m0, s40, 0x2000
	s_add_u32 s38, s38, 0x100080
	s_addc_u32 s39, s39, 0
	s_add_i32 s40, s91, s48
	global_load_lds_dwordx4 v172, s[36:37]
	s_mov_b32 m0, s40
	s_nop 0
	global_load_lds_dwordx4 v192, s[38:39]
	s_add_i32 m0, s40, 0x2000
	s_nop 0
	global_load_lds_dwordx4 v172, s[38:39]
	s_mov_b32 m0, s62
	s_nop 0
	global_load_lds_dwordx4 v168, s[98:99]
	s_mov_b32 m0, s63
	s_nop 0
	global_load_lds_dwordx4 v170, s[98:99]
	s_waitcnt vmcnt(8)
	s_waitcnt lgkmcnt(0)
	s_barrier
	s_setprio 1
	v_mfma_f32_16x16x32_bf16 v[92:95], v[120:123], v[160:163], v[92:95]
	v_mfma_f32_16x16x32_bf16 v[88:91], v[136:139], v[160:163], v[88:91]
	v_mfma_f32_16x16x32_bf16 v[84:87], v[120:123], v[178:181], v[84:87]
	v_mfma_f32_16x16x32_bf16 v[80:83], v[136:139], v[178:181], v[80:83]
	v_mfma_f32_16x16x32_bf16 v[76:79], v[120:123], v[186:189], v[76:79]
	v_mfma_f32_16x16x32_bf16 v[72:75], v[136:139], v[186:189], v[72:75]
	v_mfma_f32_16x16x32_bf16 v[68:71], v[120:123], v[208:211], v[68:71]
	v_mfma_f32_16x16x32_bf16 v[64:67], v[136:139], v[208:211], v[64:67]
	v_mfma_f32_16x16x32_bf16 v[92:95], v[124:127], v[164:167], v[92:95]
	v_mfma_f32_16x16x32_bf16 v[88:91], v[140:143], v[164:167], v[88:91]
	v_mfma_f32_16x16x32_bf16 v[84:87], v[124:127], v[182:185], v[84:87]
	v_mfma_f32_16x16x32_bf16 v[80:83], v[140:143], v[182:185], v[80:83]
	v_mfma_f32_16x16x32_bf16 v[76:79], v[124:127], v[204:207], v[76:79]
	v_mfma_f32_16x16x32_bf16 v[72:75], v[140:143], v[204:207], v[72:75]
	v_mfma_f32_16x16x32_bf16 v[68:71], v[124:127], v[212:215], v[68:71]
	v_mfma_f32_16x16x32_bf16 v[64:67], v[140:143], v[212:215], v[64:67]
	s_setprio 0
	s_setprio 1
	v_mfma_f32_16x16x32_bf16 v[28:31], v[144:147], v[160:163], v[28:31]
	v_mfma_f32_16x16x32_bf16 v[24:27], v[152:155], v[160:163], v[24:27]
	v_mfma_f32_16x16x32_bf16 v[20:23], v[144:147], v[178:181], v[20:23]
	v_mfma_f32_16x16x32_bf16 v[16:19], v[152:155], v[178:181], v[16:19]
	v_mfma_f32_16x16x32_bf16 v[12:15], v[144:147], v[186:189], v[12:15]
	v_mfma_f32_16x16x32_bf16 v[8:11], v[152:155], v[186:189], v[8:11]
	v_mfma_f32_16x16x32_bf16 v[4:7], v[144:147], v[208:211], v[4:7]
	v_mfma_f32_16x16x32_bf16 v[0:3], v[152:155], v[208:211], v[0:3]
	v_mfma_f32_16x16x32_bf16 v[28:31], v[148:151], v[164:167], v[28:31]
	v_mfma_f32_16x16x32_bf16 v[24:27], v[156:159], v[164:167], v[24:27]
	v_mfma_f32_16x16x32_bf16 v[20:23], v[148:151], v[182:185], v[20:23]
	v_mfma_f32_16x16x32_bf16 v[16:19], v[156:159], v[182:185], v[16:19]
	v_mfma_f32_16x16x32_bf16 v[12:15], v[148:151], v[204:207], v[12:15]
	v_mfma_f32_16x16x32_bf16 v[8:11], v[156:159], v[204:207], v[8:11]
	v_mfma_f32_16x16x32_bf16 v[4:7], v[148:151], v[212:215], v[4:7]
	v_mfma_f32_16x16x32_bf16 v[0:3], v[156:159], v[212:215], v[0:3]
	s_setprio 0
	s_barrier
	s_add_i32 s89, s89, 2
	s_add_u32 s4, s4, 0x100
	s_addc_u32 s5, s5, 0
	s_add_u32 s64, s64, 0x100
	s_addc_u32 s65, s65, 0
	s_cmp_gt_u32 s89, 13
	s_cbranch_scc0 .LBB0_1154
	s_and_b64 vcc, exec, s[20:21]
	s_cbranch_vccz .LBB0_1157
	s_barrier

; #define PG8_STAGE(bufoff, gbase, voff) do { _Pragma("unroll") for (int _i = 0; _i < 2; ++_i) \
;         __builtin_amdgcn_global_load_lds((const unsigned*)((const char*)(gbase) + (voff)[_i]), (LAS unsigned*)(lds + (bufoff) + ldsw + _i * 8192), 16, 0, 0); } while (0)
; #define PG8_LDA(dst, b, h) do { _Pragma("unroll") for (int m = 0; m < 4; ++m) _Pragma("unroll") for (int k = 0; k < 2; ++k) dst[m][k] = *(const LAS bf16x8*)(lds + PG8_SA(b, h) + aoff + m * 2048 + k * 1024); } while (0)
; #define PG8_LDB(dst, b, h) do { _Pragma("unroll") for (int n = 0; n < 2; ++n) _Pragma("unroll") for (int k = 0; k < 2; ++k) dst[n][k] = *(const LAS bf16x8*)(lds + PG8_SB(b, h) + boff + n * 2048 + k * 1024); } while (0)
; #define PG8_MMA(ai, bj, At, Bt) do { __builtin_amdgcn_s_setprio(1); _Pragma("unroll") for (int m = 0; m < 4; ++m) _Pragma("unroll") for (int n = 0; n < 2; ++n) _Pragma("unroll") for (int k = 0; k < 2; ++k) \
;         acc[ai][bj][m][n] = __builtin_amdgcn_mfma_f32_16x16x32_bf16(Bt[n][k], At[m][k], acc[ai][bj][m][n], 0, 0, 0); __builtin_amdgcn_s_setprio(0); } while (0)
; #define PG8_WAIT_V(n) asm volatile("s_waitcnt vmcnt(" #n ")" ::: "memory")
; template <class EpiT, class Sched>
; __device__ __forceinline__ void gemm_phase(LAS unsigned char* lds, const Gemm g, const Sched& S, const EpiT& E, int wv) {
;     ...
;         const char* nA = has_next ? (const char*)g.A + (size_t)nxt.pm * tstepA + (size_t)(nxt.pn >> g.zshift) * g.zA : cA; const char* nB = has_next ? (const char*)g.Bt + (size_t)nxt.pn * tstepB : cB;
;         for (int t = 0; t < nt; t += 2) {
;             const bool last = (t == nt - 2);
;             const char* a1 = cA + (size_t)(t + 1) * kstep;
;             const char* a2 = last ? nA : cA + (size_t)(t + 2) * kstep; const char* b2 = last ? nB : cB + (size_t)(t + 2) * kstep;
;             const char* a3 = a2 + kstep; const char* b3 = b2 + kstep;
;             PG8_LDB(B0, 0, 0); PG8_LDB(B1, 0, 1); PG8_SCHED; PG8_LDA(At, 0, 0); PG8_STAGE(PG8_SA(1, 1), a1 + hstepA, voffA);
;             PG8_WAIT_V(8); PG8_WAIT_L(0); PG8_BAR; PG8_MMA(0, 0, At, B0); PG8_MMA(0, 1, At, B1); PG8_BAR; PG8_SCHED;
;             PG8_LDA(At, 0, 1); PG8_STAGE(PG8_SB(0, 0), b2, voffB); PG8_STAGE(PG8_SB(0, 1), b2 + hstepB, voffB); PG8_STAGE(PG8_SA(0, 0), a2, voffA);
;             PG8_WAIT_V(8); PG8_WAIT_L(0); PG8_BAR; PG8_MMA(1, 0, At, B0); PG8_MMA(1, 1, At, B1); PG8_BAR; PG8_SCHED;
.LBB0_1271:
	s_add_u32 s24, s22, 0xfffc0080
	s_addc_u32 s25, s23, -1
	s_add_i32 s56, 0, 0x10000
	s_cmp_eq_u32 s55, 12
	s_cselect_b32 s27, s13, s25
	s_cselect_b32 s26, s51, s24
	s_cselect_b32 s25, s11, s54
	s_cselect_b32 s24, s52, s53
	s_add_i32 s58, 0, 0x14000
	ds_read_b128 v[128:131], v250
	ds_read_b128 v[132:135], v250 offset:1024
	ds_read_b128 v[146:149], v250 offset:2048
	ds_read_b128 v[150:153], v250 offset:3072
	ds_read_b128 v[154:157], v251
	ds_read_b128 v[160:163], v251 offset:1024
	ds_read_b128 v[164:167], v251 offset:2048
	ds_read_b128 v[168:171], v251 offset:3072
	s_add_i32 m0, s19, 0xc000
	ds_read_b128 v[172:175], v159
	ds_read_b128 v[176:179], v159 offset:1024
	ds_read_b128 v[180:183], v159 offset:2048
	ds_read_b128 v[184:187], v159 offset:3072
	ds_read_b128 v[188:191], v159 offset:4096
	ds_read_b128 v[204:207], v159 offset:5120
	ds_read_b128 v[208:211], v159 offset:6144
	ds_read_b128 v[212:215], v159 offset:7168
	global_load_lds_dwordx4 v142, s[22:23]
	s_add_i32 m0, s19, 0xe000
	s_nop 0
	global_load_lds_dwordx4 v144, s[22:23]
	s_waitcnt vmcnt(8)
	s_waitcnt lgkmcnt(0)
	s_barrier
	s_setprio 1
	v_mfma_f32_16x16x32_bf16 v[124:127], v[128:131], v[172:175], v[124:127]
	v_mfma_f32_16x16x32_bf16 v[120:123], v[146:149], v[172:175], v[120:123]
	v_mfma_f32_16x16x32_bf16 v[116:119], v[128:131], v[180:183], v[116:119]
	v_mfma_f32_16x16x32_bf16 v[112:115], v[146:149], v[180:183], v[112:115]
	v_mfma_f32_16x16x32_bf16 v[108:111], v[128:131], v[188:191], v[108:111]
	v_mfma_f32_16x16x32_bf16 v[104:107], v[146:149], v[188:191], v[104:107]
	v_mfma_f32_16x16x32_bf16 v[100:103], v[128:131], v[208:211], v[100:103]
	v_mfma_f32_16x16x32_bf16 v[96:99], v[146:149], v[208:211], v[96:99]
	v_mfma_f32_16x16x32_bf16 v[124:127], v[132:135], v[176:179], v[124:127]
	v_mfma_f32_16x16x32_bf16 v[120:123], v[150:153], v[176:179], v[120:123]
	v_mfma_f32_16x16x32_bf16 v[116:119], v[132:135], v[184:187], v[116:119]
	v_mfma_f32_16x16x32_bf16 v[112:115], v[150:153], v[184:187], v[112:115]
	v_mfma_f32_16x16x32_bf16 v[108:111], v[132:135], v[204:207], v[108:111]
	v_mfma_f32_16x16x32_bf16 v[104:107], v[150:153], v[204:207], v[104:107]
	v_mfma_f32_16x16x32_bf16 v[100:103], v[132:135], v[212:215], v[100:103]
	v_mfma_f32_16x16x32_bf16 v[96:99], v[150:153], v[212:215], v[96:99]
	s_setprio 0
	s_setprio 1
	v_mfma_f32_16x16x32_bf16 v[68:71], v[154:157], v[172:175], v[68:71]
	v_mfma_f32_16x16x32_bf16 v[64:67], v[164:167], v[172:175], v[64:67]
	v_mfma_f32_16x16x32_bf16 v[52:55], v[154:157], v[180:183], v[52:55]
	v_mfma_f32_16x16x32_bf16 v[48:51], v[164:167], v[180:183], v[48:51]
	v_mfma_f32_16x16x32_bf16 v[44:47], v[154:157], v[188:191], v[44:47]
	v_mfma_f32_16x16x32_bf16 v[40:43], v[164:167], v[188:191], v[40:43]
	v_mfma_f32_16x16x32_bf16 v[36:39], v[154:157], v[208:211], v[36:39]
	v_mfma_f32_16x16x32_bf16 v[32:35], v[164:167], v[208:211], v[32:35]
	v_mfma_f32_16x16x32_bf16 v[68:71], v[160:163], v[176:179], v[68:71]
	v_mfma_f32_16x16x32_bf16 v[64:67], v[168:171], v[176:179], v[64:67]
	v_mfma_f32_16x16x32_bf16 v[52:55], v[160:163], v[184:187], v[52:55]
	v_mfma_f32_16x16x32_bf16 v[48:51], v[168:171], v[184:187], v[48:51]
	v_mfma_f32_16x16x32_bf16 v[44:47], v[160:163], v[204:207], v[44:47]
	v_mfma_f32_16x16x32_bf16 v[40:43], v[168:171], v[204:207], v[40:43]
	v_mfma_f32_16x16x32_bf16 v[36:39], v[160:163], v[212:215], v[36:39]
	v_mfma_f32_16x16x32_bf16 v[32:35], v[168:171], v[212:215], v[32:35]
	s_setprio 0
	s_barrier
	s_add_i32 s56, s56, s33
	s_add_u32 s62, s24, s92
	s_addc_u32 s63, s25, s93
	s_mov_b32 m0, s56
	ds_read_b128 v[172:175], v159 offset:16384
	ds_read_b128 v[176:179], v159 offset:17408
	ds_read_b128 v[180:183], v159 offset:18432
	ds_read_b128 v[184:187], v159 offset:19456
	ds_read_b128 v[188:191], v159 offset:20480
	ds_read_b128 v[204:207], v159 offset:21504
	ds_read_b128 v[208:211], v159 offset:22528
	ds_read_b128 v[212:215], v159 offset:23552
	global_load_lds_dwordx4 v192, s[24:25]
	s_add_i32 m0, s56, 0x2000
	s_add_u32 s56, s24, 0x40000
	s_addc_u32 s57, s25, 0
	s_add_i32 s58, s58, s33
	global_load_lds_dwordx4 v140, s[24:25]
	s_mov_b32 m0, s58
	s_nop 0
	global_load_lds_dwordx4 v192, s[56:57]
	s_add_i32 m0, s58, 0x2000
	s_nop 0
	global_load_lds_dwordx4 v140, s[56:57]
	s_add_u32 s64, s26, s92
	s_addc_u32 s65, s27, s93
	s_mov_b32 m0, s19
	s_nop 0
	global_load_lds_dwordx4 v136, s[26:27]
	s_mov_b32 m0, s21
	s_nop 0
	global_load_lds_dwordx4 v138, s[26:27]
	s_waitcnt vmcnt(8)
	s_waitcnt lgkmcnt(0)
	s_barrier
	s_setprio 1
	v_mfma_f32_16x16x32_bf16 v[92:95], v[128:131], v[172:175], v[92:95]
	v_mfma_f32_16x16x32_bf16 v[88:91], v[146:149], v[172:175], v[88:91]
	v_mfma_f32_16x16x32_bf16 v[84:87], v[128:131], v[180:183], v[84:87]
	v_mfma_f32_16x16x32_bf16 v[80:83], v[146:149], v[180:183], v[80:83]
	v_mfma_f32_16x16x32_bf16 v[76:79], v[128:131], v[188:191], v[76:79]
	v_mfma_f32_16x16x32_bf16 v[72:75], v[146:149], v[188:191], v[72:75]
	v_mfma_f32_16x16x32_bf16 v[60:63], v[128:131], v[208:211], v[60:63]
	v_mfma_f32_16x16x32_bf16 v[56:59], v[146:149], v[208:211], v[56:59]
	v_mfma_f32_16x16x32_bf16 v[92:95], v[132:135], v[176:179], v[92:95]
	v_mfma_f32_16x16x32_bf16 v[88:91], v[150:153], v[176:179], v[88:91]
	v_mfma_f32_16x16x32_bf16 v[84:87], v[132:135], v[184:187], v[84:87]
	v_mfma_f32_16x16x32_bf16 v[80:83], v[150:153], v[184:187], v[80:83]
	v_mfma_f32_16x16x32_bf16 v[76:79], v[132:135], v[204:207], v[76:79]
	v_mfma_f32_16x16x32_bf16 v[72:75], v[150:153], v[204:207], v[72:75]
	v_mfma_f32_16x16x32_bf16 v[60:63], v[132:135], v[212:215], v[60:63]
	v_mfma_f32_16x16x32_bf16 v[56:59], v[150:153], v[212:215], v[56:59]
	s_setprio 0
	s_setprio 1
	v_mfma_f32_16x16x32_bf16 v[28:31], v[154:157], v[172:175], v[28:31]
	v_mfma_f32_16x16x32_bf16 v[24:27], v[164:167], v[172:175], v[24:27]
	v_mfma_f32_16x16x32_bf16 v[20:23], v[154:157], v[180:183], v[20:23]
	v_mfma_f32_16x16x32_bf16 v[16:19], v[164:167], v[180:183], v[16:19]
	v_mfma_f32_16x16x32_bf16 v[12:15], v[154:157], v[188:191], v[12:15]
	v_mfma_f32_16x16x32_bf16 v[8:11], v[164:167], v[188:191], v[8:11]
	v_mfma_f32_16x16x32_bf16 v[4:7], v[154:157], v[208:211], v[4:7]
	v_mfma_f32_16x16x32_bf16 v[0:3], v[164:167], v[208:211], v[0:3]
	v_mfma_f32_16x16x32_bf16 v[28:31], v[160:163], v[176:179], v[28:31]
	v_mfma_f32_16x16x32_bf16 v[24:27], v[168:171], v[176:179], v[24:27]
	v_mfma_f32_16x16x32_bf16 v[20:23], v[160:163], v[184:187], v[20:23]
	v_mfma_f32_16x16x32_bf16 v[16:19], v[168:171], v[184:187], v[16:19]
	v_mfma_f32_16x16x32_bf16 v[12:15], v[160:163], v[204:207], v[12:15]
	v_mfma_f32_16x16x32_bf16 v[8:11], v[168:171], v[204:207], v[8:11]
	v_mfma_f32_16x16x32_bf16 v[4:7], v[160:163], v[212:215], v[4:7]
	v_mfma_f32_16x16x32_bf16 v[0:3], v[168:171], v[212:215], v[0:3]
	s_setprio 0
	s_barrier
; #define PG8_STAGE(bufoff, gbase, voff) do { _Pragma("unroll") for (int _i = 0; _i < 2; ++_i) \
;         __builtin_amdgcn_global_load_lds((const unsigned*)((const char*)(gbase) + (voff)[_i]), (LAS unsigned*)(lds + (bufoff) + ldsw + _i * 8192), 16, 0, 0); } while (0)
; #define PG8_LDA(dst, b, h) do { _Pragma("unroll") for (int m = 0; m < 4; ++m) _Pragma("unroll") for (int k = 0; k < 2; ++k) dst[m][k] = *(const LAS bf16x8*)(lds + PG8_SA(b, h) + aoff + m * 2048 + k * 1024); } while (0)
; #define PG8_LDB(dst, b, h) do { _Pragma("unroll") for (int n = 0; n < 2; ++n) _Pragma("unroll") for (int k = 0; k < 2; ++k) dst[n][k] = *(const LAS bf16x8*)(lds + PG8_SB(b, h) + boff + n * 2048 + k * 1024); } while (0)
; #define PG8_MMA(ai, bj, At, Bt) do { __builtin_amdgcn_s_setprio(1); _Pragma("unroll") for (int m = 0; m < 4; ++m) _Pragma("unroll") for (int n = 0; n < 2; ++n) _Pragma("unroll") for (int k = 0; k < 2; ++k) \
;         acc[ai][bj][m][n] = __builtin_amdgcn_mfma_f32_16x16x32_bf16(Bt[n][k], At[m][k], acc[ai][bj][m][n], 0, 0, 0); __builtin_amdgcn_s_setprio(0); } while (0)
; #define PG8_WAIT_V(n) asm volatile("s_waitcnt vmcnt(" #n ")" ::: "memory")
; #define PG8_WAIT_L(n) asm volatile("s_waitcnt lgkmcnt(" #n ")" ::: "memory")
; #define PG8_BAR __builtin_amdgcn_s_barrier()
; #define PG8_SCHED __builtin_amdgcn_sched_barrier(0)
; template <class EpiT, class Sched>
; __device__ __forceinline__ void gemm_phase(LAS unsigned char* lds, const Gemm g, const Sched& S, const EpiT& E, int wv) {
;     ...
;             PG8_LDB(B0, 1, 0); PG8_LDB(B1, 1, 1); PG8_SCHED; PG8_LDA(At, 1, 0); PG8_STAGE(PG8_SA(0, 1), a2 + hstepA, voffA);
;             PG8_WAIT_V(8); PG8_WAIT_L(0); PG8_BAR; PG8_MMA(0, 0, At, B0); PG8_MMA(0, 1, At, B1); PG8_BAR; PG8_SCHED;
;             PG8_LDA(At, 1, 1); PG8_STAGE(PG8_SB(1, 0), b3, voffB); PG8_STAGE(PG8_SB(1, 1), b3 + hstepB, voffB); PG8_STAGE(PG8_SA(1, 0), a3, voffA);
;             PG8_WAIT_V(8); PG8_WAIT_L(0); PG8_BAR; PG8_MMA(1, 0, At, B0); PG8_MMA(1, 1, At, B1); PG8_BAR; PG8_SCHED;
;         }
;         if (wr == 0) PG8_BAR;
	s_add_i32 s56, 0, 0x18000
	s_add_i32 s57, 0, 0x1c000
	ds_read_b128 v[128:131], v252
	ds_read_b128 v[132:135], v252 offset:1024
	ds_read_b128 v[146:149], v252 offset:2048
	ds_read_b128 v[150:153], v252 offset:3072
	ds_read_b128 v[154:157], v253
	ds_read_b128 v[160:163], v253 offset:1024
	ds_read_b128 v[164:167], v253 offset:2048
	ds_read_b128 v[168:171], v253 offset:3072
	s_add_u32 s26, s26, 0x40000
	s_addc_u32 s27, s27, 0
	s_mov_b32 m0, s38
	ds_read_b128 v[172:175], v159 offset:32768
	ds_read_b128 v[176:179], v159 offset:33792
	ds_read_b128 v[180:183], v159 offset:34816
	ds_read_b128 v[184:187], v159 offset:35840
	ds_read_b128 v[188:191], v159 offset:36864
	ds_read_b128 v[204:207], v159 offset:37888
	ds_read_b128 v[208:211], v159 offset:38912
	ds_read_b128 v[212:215], v159 offset:39936
	global_load_lds_dwordx4 v136, s[26:27]
	s_mov_b32 m0, s39
	s_nop 0
	global_load_lds_dwordx4 v138, s[26:27]
	s_waitcnt vmcnt(8)
	s_waitcnt lgkmcnt(0)
	s_barrier
	s_setprio 1
	v_mfma_f32_16x16x32_bf16 v[124:127], v[128:131], v[172:175], v[124:127]
	v_mfma_f32_16x16x32_bf16 v[120:123], v[146:149], v[172:175], v[120:123]
	v_mfma_f32_16x16x32_bf16 v[116:119], v[128:131], v[180:183], v[116:119]
	v_mfma_f32_16x16x32_bf16 v[112:115], v[146:149], v[180:183], v[112:115]
	v_mfma_f32_16x16x32_bf16 v[108:111], v[128:131], v[188:191], v[108:111]
	v_mfma_f32_16x16x32_bf16 v[104:107], v[146:149], v[188:191], v[104:107]
	v_mfma_f32_16x16x32_bf16 v[100:103], v[128:131], v[208:211], v[100:103]
	v_mfma_f32_16x16x32_bf16 v[96:99], v[146:149], v[208:211], v[96:99]
	v_mfma_f32_16x16x32_bf16 v[124:127], v[132:135], v[176:179], v[124:127]
	v_mfma_f32_16x16x32_bf16 v[120:123], v[150:153], v[176:179], v[120:123]
	v_mfma_f32_16x16x32_bf16 v[116:119], v[132:135], v[184:187], v[116:119]
	v_mfma_f32_16x16x32_bf16 v[112:115], v[150:153], v[184:187], v[112:115]
	v_mfma_f32_16x16x32_bf16 v[108:111], v[132:135], v[204:207], v[108:111]
	v_mfma_f32_16x16x32_bf16 v[104:107], v[150:153], v[204:207], v[104:107]
	v_mfma_f32_16x16x32_bf16 v[100:103], v[132:135], v[212:215], v[100:103]
	v_mfma_f32_16x16x32_bf16 v[96:99], v[150:153], v[212:215], v[96:99]
	s_setprio 0
	s_setprio 1
	v_mfma_f32_16x16x32_bf16 v[68:71], v[154:157], v[172:175], v[68:71]
	v_mfma_f32_16x16x32_bf16 v[64:67], v[164:167], v[172:175], v[64:67]
	v_mfma_f32_16x16x32_bf16 v[52:55], v[154:157], v[180:183], v[52:55]
	v_mfma_f32_16x16x32_bf16 v[48:51], v[164:167], v[180:183], v[48:51]
	v_mfma_f32_16x16x32_bf16 v[44:47], v[154:157], v[188:191], v[44:47]
	v_mfma_f32_16x16x32_bf16 v[40:43], v[164:167], v[188:191], v[40:43]
	v_mfma_f32_16x16x32_bf16 v[36:39], v[154:157], v[208:211], v[36:39]
	v_mfma_f32_16x16x32_bf16 v[32:35], v[164:167], v[208:211], v[32:35]
	v_mfma_f32_16x16x32_bf16 v[68:71], v[160:163], v[176:179], v[68:71]
	v_mfma_f32_16x16x32_bf16 v[64:67], v[168:171], v[176:179], v[64:67]
	v_mfma_f32_16x16x32_bf16 v[52:55], v[160:163], v[184:187], v[52:55]
	v_mfma_f32_16x16x32_bf16 v[48:51], v[168:171], v[184:187], v[48:51]
	v_mfma_f32_16x16x32_bf16 v[44:47], v[160:163], v[204:207], v[44:47]
	v_mfma_f32_16x16x32_bf16 v[40:43], v[168:171], v[204:207], v[40:43]
	v_mfma_f32_16x16x32_bf16 v[36:39], v[160:163], v[212:215], v[36:39]
	v_mfma_f32_16x16x32_bf16 v[32:35], v[168:171], v[212:215], v[32:35]
	s_setprio 0
	s_barrier
	s_add_i32 s26, s56, s33
	s_mov_b32 m0, s26
	ds_read_b128 v[172:175], v159 offset:49152
	ds_read_b128 v[176:179], v159 offset:50176
	ds_read_b128 v[180:183], v159 offset:51200
	ds_read_b128 v[184:187], v159 offset:52224
	ds_read_b128 v[188:191], v159 offset:53248
	ds_read_b128 v[204:207], v159 offset:54272
	ds_read_b128 v[208:211], v159 offset:55296
	ds_read_b128 v[212:215], v159 offset:56320
	global_load_lds_dwordx4 v192, s[62:63]
	s_add_i32 m0, s26, 0x2000
	s_add_u32 s24, s24, 0x40080
	s_addc_u32 s25, s25, 0
	s_add_i32 s26, s57, s33
	global_load_lds_dwordx4 v140, s[62:63]
	s_mov_b32 m0, s26
	s_nop 0
	global_load_lds_dwordx4 v192, s[24:25]
	s_add_i32 m0, s26, 0x2000
	s_nop 0
	global_load_lds_dwordx4 v140, s[24:25]
	s_mov_b32 m0, s40
	s_nop 0
	global_load_lds_dwordx4 v136, s[64:65]
	s_mov_b32 m0, s41
	s_nop 0
	global_load_lds_dwordx4 v138, s[64:65]
	s_waitcnt vmcnt(8)
	s_waitcnt lgkmcnt(0)
	s_barrier
	s_setprio 1
	v_mfma_f32_16x16x32_bf16 v[92:95], v[128:131], v[172:175], v[92:95]
	v_mfma_f32_16x16x32_bf16 v[88:91], v[146:149], v[172:175], v[88:91]
	v_mfma_f32_16x16x32_bf16 v[84:87], v[128:131], v[180:183], v[84:87]
	v_mfma_f32_16x16x32_bf16 v[80:83], v[146:149], v[180:183], v[80:83]
	v_mfma_f32_16x16x32_bf16 v[76:79], v[128:131], v[188:191], v[76:79]
	v_mfma_f32_16x16x32_bf16 v[72:75], v[146:149], v[188:191], v[72:75]
	v_mfma_f32_16x16x32_bf16 v[60:63], v[128:131], v[208:211], v[60:63]
	v_mfma_f32_16x16x32_bf16 v[56:59], v[146:149], v[208:211], v[56:59]
	v_mfma_f32_16x16x32_bf16 v[92:95], v[132:135], v[176:179], v[92:95]
	v_mfma_f32_16x16x32_bf16 v[88:91], v[150:153], v[176:179], v[88:91]
	v_mfma_f32_16x16x32_bf16 v[84:87], v[132:135], v[184:187], v[84:87]
	v_mfma_f32_16x16x32_bf16 v[80:83], v[150:153], v[184:187], v[80:83]
	v_mfma_f32_16x16x32_bf16 v[76:79], v[132:135], v[204:207], v[76:79]
	v_mfma_f32_16x16x32_bf16 v[72:75], v[150:153], v[204:207], v[72:75]
	v_mfma_f32_16x16x32_bf16 v[60:63], v[132:135], v[212:215], v[60:63]
	v_mfma_f32_16x16x32_bf16 v[56:59], v[150:153], v[212:215], v[56:59]
	s_setprio 0
	s_setprio 1
	v_mfma_f32_16x16x32_bf16 v[28:31], v[154:157], v[172:175], v[28:31]
	v_mfma_f32_16x16x32_bf16 v[24:27], v[164:167], v[172:175], v[24:27]
	v_mfma_f32_16x16x32_bf16 v[20:23], v[154:157], v[180:183], v[20:23]
	v_mfma_f32_16x16x32_bf16 v[16:19], v[164:167], v[180:183], v[16:19]
	v_mfma_f32_16x16x32_bf16 v[12:15], v[154:157], v[188:191], v[12:15]
	v_mfma_f32_16x16x32_bf16 v[8:11], v[164:167], v[188:191], v[8:11]
	v_mfma_f32_16x16x32_bf16 v[4:7], v[154:157], v[208:211], v[4:7]
	v_mfma_f32_16x16x32_bf16 v[0:3], v[164:167], v[208:211], v[0:3]
	v_mfma_f32_16x16x32_bf16 v[28:31], v[160:163], v[176:179], v[28:31]
	v_mfma_f32_16x16x32_bf16 v[24:27], v[168:171], v[176:179], v[24:27]
	v_mfma_f32_16x16x32_bf16 v[20:23], v[160:163], v[184:187], v[20:23]
	v_mfma_f32_16x16x32_bf16 v[16:19], v[168:171], v[184:187], v[16:19]
	v_mfma_f32_16x16x32_bf16 v[12:15], v[160:163], v[204:207], v[12:15]
	v_mfma_f32_16x16x32_bf16 v[8:11], v[168:171], v[204:207], v[8:11]
	v_mfma_f32_16x16x32_bf16 v[4:7], v[160:163], v[212:215], v[4:7]
	v_mfma_f32_16x16x32_bf16 v[0:3], v[168:171], v[212:215], v[0:3]
	s_setprio 0
	s_barrier
	s_add_i32 s55, s55, 2
	s_add_u32 s22, s22, 0x100
	s_addc_u32 s23, s23, 0
	s_add_u32 s53, s53, 0x100
	s_addc_u32 s54, s54, 0
	s_cmp_gt_u32 s55, 13
	s_cbranch_scc0 .LBB0_1271
	s_and_b64 vcc, exec, s[8:9]
	s_cbranch_vccz .LBB0_1274
	s_barrier

; #define PG8_STAGE(bufoff, gbase, voff) do { _Pragma("unroll") for (int _i = 0; _i < 2; ++_i) \
;         __builtin_amdgcn_global_load_lds((const unsigned*)((const char*)(gbase) + (voff)[_i]), (LAS unsigned*)(lds + (bufoff) + ldsw + _i * 8192), 16, 0, 0); } while (0)
; #define PG8_LDA(dst, b, h) do { _Pragma("unroll") for (int m = 0; m < 4; ++m) _Pragma("unroll") for (int k = 0; k < 2; ++k) dst[m][k] = *(const LAS bf16x8*)(lds + PG8_SA(b, h) + aoff + m * 2048 + k * 1024); } while (0)
; #define PG8_LDB(dst, b, h) do { _Pragma("unroll") for (int n = 0; n < 2; ++n) _Pragma("unroll") for (int k = 0; k < 2; ++k) dst[n][k] = *(const LAS bf16x8*)(lds + PG8_SB(b, h) + boff + n * 2048 + k * 1024); } while (0)
; #define PG8_MMA(ai, bj, At, Bt) do { __builtin_amdgcn_s_setprio(1); _Pragma("unroll") for (int m = 0; m < 4; ++m) _Pragma("unroll") for (int n = 0; n < 2; ++n) _Pragma("unroll") for (int k = 0; k < 2; ++k) \
;         acc[ai][bj][m][n] = __builtin_amdgcn_mfma_f32_16x16x32_bf16(Bt[n][k], At[m][k], acc[ai][bj][m][n], 0, 0, 0); __builtin_amdgcn_s_setprio(0); } while (0)
; #define PG8_WAIT_V(n) asm volatile("s_waitcnt vmcnt(" #n ")" ::: "memory")
; template <class EpiT, class Sched>
; __device__ __forceinline__ void gemm_phase(LAS unsigned char* lds, const Gemm g, const Sched& S, const EpiT& E, int wv) {
;     ...
;         const char* nA = has_next ? (const char*)g.A + (size_t)nxt.pm * tstepA + (size_t)(nxt.pn >> g.zshift) * g.zA : cA; const char* nB = has_next ? (const char*)g.Bt + (size_t)nxt.pn * tstepB : cB;
;         for (int t = 0; t < nt; t += 2) {
;             const bool last = (t == nt - 2);
;             const char* a1 = cA + (size_t)(t + 1) * kstep;
;             const char* a2 = last ? nA : cA + (size_t)(t + 2) * kstep; const char* b2 = last ? nB : cB + (size_t)(t + 2) * kstep;
;             const char* a3 = a2 + kstep; const char* b3 = b2 + kstep;
;             PG8_LDB(B0, 0, 0); PG8_LDB(B1, 0, 1); PG8_SCHED; PG8_LDA(At, 0, 0); PG8_STAGE(PG8_SA(1, 1), a1 + hstepA, voffA);
;             PG8_WAIT_V(8); PG8_WAIT_L(0); PG8_BAR; PG8_MMA(0, 0, At, B0); PG8_MMA(0, 1, At, B1); PG8_BAR; PG8_SCHED;
;             PG8_LDA(At, 0, 1); PG8_STAGE(PG8_SB(0, 0), b2, voffB); PG8_STAGE(PG8_SB(0, 1), b2 + hstepB, voffB); PG8_STAGE(PG8_SA(0, 0), a2, voffA);
;             PG8_WAIT_V(8); PG8_WAIT_L(0); PG8_BAR; PG8_MMA(1, 0, At, B0); PG8_MMA(1, 1, At, B1); PG8_BAR; PG8_SCHED;
.LBB0_1335:
	s_add_u32 s24, s4, 0xfff00080
	s_addc_u32 s25, s5, -1
	s_add_i32 s62, 0, 0x10000
	s_cmp_eq_u32 s59, 60
	s_cselect_b32 s27, s17, s25
	s_cselect_b32 s26, s19, s24
	s_cselect_b32 s25, s11, s58
	s_cselect_b32 s24, s23, s33
	s_add_i32 s64, 0, 0x14000
	ds_read_b128 v[128:131], v250
	ds_read_b128 v[132:135], v250 offset:1024
	ds_read_b128 v[136:139], v250 offset:2048
	ds_read_b128 v[140:143], v250 offset:3072
	ds_read_b128 v[144:147], v251
	ds_read_b128 v[148:151], v251 offset:1024
	ds_read_b128 v[152:155], v251 offset:2048
	ds_read_b128 v[156:159], v251 offset:3072
	s_add_i32 m0, s38, 0xc000
	ds_read_b128 v[160:163], v215
	ds_read_b128 v[164:167], v215 offset:1024
	ds_read_b128 v[178:181], v215 offset:2048
	ds_read_b128 v[182:185], v215 offset:3072
	ds_read_b128 v[186:189], v215 offset:4096
	ds_read_b128 v[204:207], v215 offset:5120
	ds_read_b128 v[208:211], v215 offset:6144
	ds_read_b128 v[216:219], v215 offset:7168
	global_load_lds_dwordx4 v174, s[4:5]
	s_add_i32 m0, s38, 0xe000
	s_nop 0
	global_load_lds_dwordx4 v176, s[4:5]
	s_waitcnt vmcnt(8)
	s_waitcnt lgkmcnt(0)
	s_barrier
	s_setprio 1
	v_mfma_f32_16x16x32_bf16 v[124:127], v[128:131], v[160:163], v[124:127]
	v_mfma_f32_16x16x32_bf16 v[120:123], v[136:139], v[160:163], v[120:123]
	v_mfma_f32_16x16x32_bf16 v[116:119], v[128:131], v[178:181], v[116:119]
	v_mfma_f32_16x16x32_bf16 v[112:115], v[136:139], v[178:181], v[112:115]
	v_mfma_f32_16x16x32_bf16 v[108:111], v[128:131], v[186:189], v[108:111]
	v_mfma_f32_16x16x32_bf16 v[104:107], v[136:139], v[186:189], v[104:107]
	v_mfma_f32_16x16x32_bf16 v[100:103], v[128:131], v[208:211], v[100:103]
	v_mfma_f32_16x16x32_bf16 v[96:99], v[136:139], v[208:211], v[96:99]
	v_mfma_f32_16x16x32_bf16 v[124:127], v[132:135], v[164:167], v[124:127]
	v_mfma_f32_16x16x32_bf16 v[120:123], v[140:143], v[164:167], v[120:123]
	v_mfma_f32_16x16x32_bf16 v[116:119], v[132:135], v[182:185], v[116:119]
	v_mfma_f32_16x16x32_bf16 v[112:115], v[140:143], v[182:185], v[112:115]
	v_mfma_f32_16x16x32_bf16 v[108:111], v[132:135], v[204:207], v[108:111]
	v_mfma_f32_16x16x32_bf16 v[104:107], v[140:143], v[204:207], v[104:107]
	v_mfma_f32_16x16x32_bf16 v[100:103], v[132:135], v[216:219], v[100:103]
	v_mfma_f32_16x16x32_bf16 v[96:99], v[140:143], v[216:219], v[96:99]
	s_setprio 0
	s_setprio 1
	v_mfma_f32_16x16x32_bf16 v[60:63], v[144:147], v[160:163], v[60:63]
	v_mfma_f32_16x16x32_bf16 v[56:59], v[152:155], v[160:163], v[56:59]
	v_mfma_f32_16x16x32_bf16 v[52:55], v[144:147], v[178:181], v[52:55]
	v_mfma_f32_16x16x32_bf16 v[48:51], v[152:155], v[178:181], v[48:51]
	v_mfma_f32_16x16x32_bf16 v[44:47], v[144:147], v[186:189], v[44:47]
	v_mfma_f32_16x16x32_bf16 v[40:43], v[152:155], v[186:189], v[40:43]
	v_mfma_f32_16x16x32_bf16 v[36:39], v[144:147], v[208:211], v[36:39]
	v_mfma_f32_16x16x32_bf16 v[32:35], v[152:155], v[208:211], v[32:35]
	v_mfma_f32_16x16x32_bf16 v[60:63], v[148:151], v[164:167], v[60:63]
	v_mfma_f32_16x16x32_bf16 v[56:59], v[156:159], v[164:167], v[56:59]
	v_mfma_f32_16x16x32_bf16 v[52:55], v[148:151], v[182:185], v[52:55]
	v_mfma_f32_16x16x32_bf16 v[48:51], v[156:159], v[182:185], v[48:51]
	v_mfma_f32_16x16x32_bf16 v[44:47], v[148:151], v[204:207], v[44:47]
	v_mfma_f32_16x16x32_bf16 v[40:43], v[156:159], v[204:207], v[40:43]
	v_mfma_f32_16x16x32_bf16 v[36:39], v[148:151], v[216:219], v[36:39]
	v_mfma_f32_16x16x32_bf16 v[32:35], v[156:159], v[216:219], v[32:35]
	s_setprio 0
	s_barrier
	s_add_i32 s62, s62, s37
	s_add_u32 s72, s24, s92
	s_addc_u32 s73, s25, s93
	s_mov_b32 m0, s62
	ds_read_b128 v[160:163], v215 offset:16384
	ds_read_b128 v[164:167], v215 offset:17408
	ds_read_b128 v[178:181], v215 offset:18432
	ds_read_b128 v[182:185], v215 offset:19456
	ds_read_b128 v[186:189], v215 offset:20480
	ds_read_b128 v[204:207], v215 offset:21504
	ds_read_b128 v[208:211], v215 offset:22528
	ds_read_b128 v[216:219], v215 offset:23552
	global_load_lds_dwordx4 v192, s[24:25]
	s_add_i32 m0, s62, 0x2000
	s_add_u32 s62, s24, 0x100000
	s_addc_u32 s63, s25, 0
	s_add_i32 s64, s64, s37
	global_load_lds_dwordx4 v172, s[24:25]
	s_mov_b32 m0, s64
	s_nop 0
	global_load_lds_dwordx4 v192, s[62:63]
	s_add_i32 m0, s64, 0x2000
	s_nop 0
	global_load_lds_dwordx4 v172, s[62:63]
	s_add_u32 s98, s26, s92
	s_addc_u32 s99, s27, s93
	s_mov_b32 m0, s38
	s_nop 0
	global_load_lds_dwordx4 v168, s[26:27]
	s_mov_b32 m0, s39
	s_nop 0
	global_load_lds_dwordx4 v170, s[26:27]
	s_waitcnt vmcnt(8)
	s_waitcnt lgkmcnt(0)
	s_barrier
	s_setprio 1
	v_mfma_f32_16x16x32_bf16 v[92:95], v[128:131], v[160:163], v[92:95]
	v_mfma_f32_16x16x32_bf16 v[88:91], v[136:139], v[160:163], v[88:91]
	v_mfma_f32_16x16x32_bf16 v[84:87], v[128:131], v[178:181], v[84:87]
	v_mfma_f32_16x16x32_bf16 v[80:83], v[136:139], v[178:181], v[80:83]
	v_mfma_f32_16x16x32_bf16 v[76:79], v[128:131], v[186:189], v[76:79]
	v_mfma_f32_16x16x32_bf16 v[72:75], v[136:139], v[186:189], v[72:75]
	v_mfma_f32_16x16x32_bf16 v[68:71], v[128:131], v[208:211], v[68:71]
	v_mfma_f32_16x16x32_bf16 v[64:67], v[136:139], v[208:211], v[64:67]
	v_mfma_f32_16x16x32_bf16 v[92:95], v[132:135], v[164:167], v[92:95]
	v_mfma_f32_16x16x32_bf16 v[88:91], v[140:143], v[164:167], v[88:91]
	v_mfma_f32_16x16x32_bf16 v[84:87], v[132:135], v[182:185], v[84:87]
	v_mfma_f32_16x16x32_bf16 v[80:83], v[140:143], v[182:185], v[80:83]
	v_mfma_f32_16x16x32_bf16 v[76:79], v[132:135], v[204:207], v[76:79]
	v_mfma_f32_16x16x32_bf16 v[72:75], v[140:143], v[204:207], v[72:75]
	v_mfma_f32_16x16x32_bf16 v[68:71], v[132:135], v[216:219], v[68:71]
	v_mfma_f32_16x16x32_bf16 v[64:67], v[140:143], v[216:219], v[64:67]
	s_setprio 0
	s_setprio 1
	v_mfma_f32_16x16x32_bf16 v[28:31], v[144:147], v[160:163], v[28:31]
	v_mfma_f32_16x16x32_bf16 v[24:27], v[152:155], v[160:163], v[24:27]
	v_mfma_f32_16x16x32_bf16 v[20:23], v[144:147], v[178:181], v[20:23]
	v_mfma_f32_16x16x32_bf16 v[16:19], v[152:155], v[178:181], v[16:19]
	v_mfma_f32_16x16x32_bf16 v[12:15], v[144:147], v[186:189], v[12:15]
	v_mfma_f32_16x16x32_bf16 v[8:11], v[152:155], v[186:189], v[8:11]
	v_mfma_f32_16x16x32_bf16 v[4:7], v[144:147], v[208:211], v[4:7]
	v_mfma_f32_16x16x32_bf16 v[0:3], v[152:155], v[208:211], v[0:3]
	v_mfma_f32_16x16x32_bf16 v[28:31], v[148:151], v[164:167], v[28:31]
	v_mfma_f32_16x16x32_bf16 v[24:27], v[156:159], v[164:167], v[24:27]
	v_mfma_f32_16x16x32_bf16 v[20:23], v[148:151], v[182:185], v[20:23]
	v_mfma_f32_16x16x32_bf16 v[16:19], v[156:159], v[182:185], v[16:19]
	v_mfma_f32_16x16x32_bf16 v[12:15], v[148:151], v[204:207], v[12:15]
	v_mfma_f32_16x16x32_bf16 v[8:11], v[156:159], v[204:207], v[8:11]
	v_mfma_f32_16x16x32_bf16 v[4:7], v[148:151], v[216:219], v[4:7]
	v_mfma_f32_16x16x32_bf16 v[0:3], v[156:159], v[216:219], v[0:3]
	s_setprio 0
	s_barrier
; #define PG8_STAGE(bufoff, gbase, voff) do { _Pragma("unroll") for (int _i = 0; _i < 2; ++_i) \
;         __builtin_amdgcn_global_load_lds((const unsigned*)((const char*)(gbase) + (voff)[_i]), (LAS unsigned*)(lds + (bufoff) + ldsw + _i * 8192), 16, 0, 0); } while (0)
; #define PG8_LDA(dst, b, h) do { _Pragma("unroll") for (int m = 0; m < 4; ++m) _Pragma("unroll") for (int k = 0; k < 2; ++k) dst[m][k] = *(const LAS bf16x8*)(lds + PG8_SA(b, h) + aoff + m * 2048 + k * 1024); } while (0)
; #define PG8_LDB(dst, b, h) do { _Pragma("unroll") for (int n = 0; n < 2; ++n) _Pragma("unroll") for (int k = 0; k < 2; ++k) dst[n][k] = *(const LAS bf16x8*)(lds + PG8_SB(b, h) + boff + n * 2048 + k * 1024); } while (0)
; #define PG8_MMA(ai, bj, At, Bt) do { __builtin_amdgcn_s_setprio(1); _Pragma("unroll") for (int m = 0; m < 4; ++m) _Pragma("unroll") for (int n = 0; n < 2; ++n) _Pragma("unroll") for (int k = 0; k < 2; ++k) \
;         acc[ai][bj][m][n] = __builtin_amdgcn_mfma_f32_16x16x32_bf16(Bt[n][k], At[m][k], acc[ai][bj][m][n], 0, 0, 0); __builtin_amdgcn_s_setprio(0); } while (0)
; #define PG8_WAIT_V(n) asm volatile("s_waitcnt vmcnt(" #n ")" ::: "memory")
; #define PG8_WAIT_L(n) asm volatile("s_waitcnt lgkmcnt(" #n ")" ::: "memory")
; #define PG8_BAR __builtin_amdgcn_s_barrier()
; #define PG8_SCHED __builtin_amdgcn_sched_barrier(0)
; template <class EpiT, class Sched>
; __device__ __forceinline__ void gemm_phase(LAS unsigned char* lds, const Gemm g, const Sched& S, const EpiT& E, int wv) {
;     ...
;             PG8_LDB(B0, 1, 0); PG8_LDB(B1, 1, 1); PG8_SCHED; PG8_LDA(At, 1, 0); PG8_STAGE(PG8_SA(0, 1), a2 + hstepA, voffA);
;             PG8_WAIT_V(8); PG8_WAIT_L(0); PG8_BAR; PG8_MMA(0, 0, At, B0); PG8_MMA(0, 1, At, B1); PG8_BAR; PG8_SCHED;
;             PG8_LDA(At, 1, 1); PG8_STAGE(PG8_SB(1, 0), b3, voffB); PG8_STAGE(PG8_SB(1, 1), b3 + hstepB, voffB); PG8_STAGE(PG8_SA(1, 0), a3, voffA);
;             PG8_WAIT_V(8); PG8_WAIT_L(0); PG8_BAR; PG8_MMA(1, 0, At, B0); PG8_MMA(1, 1, At, B1); PG8_BAR; PG8_SCHED;
;         }
;         if (wr == 0) PG8_BAR;
	s_add_i32 s62, 0, 0x18000
	s_add_i32 s63, 0, 0x1c000
	ds_read_b128 v[128:131], v252
	ds_read_b128 v[132:135], v252 offset:1024
	ds_read_b128 v[136:139], v252 offset:2048
	ds_read_b128 v[140:143], v252 offset:3072
	ds_read_b128 v[144:147], v253
	ds_read_b128 v[148:151], v253 offset:1024
	ds_read_b128 v[152:155], v253 offset:2048
	ds_read_b128 v[156:159], v253 offset:3072
	s_add_u32 s26, s26, 0x100000
	s_addc_u32 s27, s27, 0
	s_mov_b32 m0, s40
	ds_read_b128 v[160:163], v215 offset:32768
	ds_read_b128 v[164:167], v215 offset:33792
	ds_read_b128 v[178:181], v215 offset:34816
	ds_read_b128 v[182:185], v215 offset:35840
	ds_read_b128 v[186:189], v215 offset:36864
	ds_read_b128 v[204:207], v215 offset:37888
	ds_read_b128 v[208:211], v215 offset:38912
	ds_read_b128 v[216:219], v215 offset:39936
	global_load_lds_dwordx4 v168, s[26:27]
	s_mov_b32 m0, s41
	s_nop 0
	global_load_lds_dwordx4 v170, s[26:27]
	s_waitcnt vmcnt(8)
	s_waitcnt lgkmcnt(0)
	s_barrier
	s_setprio 1
	v_mfma_f32_16x16x32_bf16 v[124:127], v[128:131], v[160:163], v[124:127]
	v_mfma_f32_16x16x32_bf16 v[120:123], v[136:139], v[160:163], v[120:123]
	v_mfma_f32_16x16x32_bf16 v[116:119], v[128:131], v[178:181], v[116:119]
	v_mfma_f32_16x16x32_bf16 v[112:115], v[136:139], v[178:181], v[112:115]
	v_mfma_f32_16x16x32_bf16 v[108:111], v[128:131], v[186:189], v[108:111]
	v_mfma_f32_16x16x32_bf16 v[104:107], v[136:139], v[186:189], v[104:107]
	v_mfma_f32_16x16x32_bf16 v[100:103], v[128:131], v[208:211], v[100:103]
	v_mfma_f32_16x16x32_bf16 v[96:99], v[136:139], v[208:211], v[96:99]
	v_mfma_f32_16x16x32_bf16 v[124:127], v[132:135], v[164:167], v[124:127]
	v_mfma_f32_16x16x32_bf16 v[120:123], v[140:143], v[164:167], v[120:123]
	v_mfma_f32_16x16x32_bf16 v[116:119], v[132:135], v[182:185], v[116:119]
	v_mfma_f32_16x16x32_bf16 v[112:115], v[140:143], v[182:185], v[112:115]
	v_mfma_f32_16x16x32_bf16 v[108:111], v[132:135], v[204:207], v[108:111]
	v_mfma_f32_16x16x32_bf16 v[104:107], v[140:143], v[204:207], v[104:107]
	v_mfma_f32_16x16x32_bf16 v[100:103], v[132:135], v[216:219], v[100:103]
	v_mfma_f32_16x16x32_bf16 v[96:99], v[140:143], v[216:219], v[96:99]
	s_setprio 0
	s_setprio 1
	v_mfma_f32_16x16x32_bf16 v[60:63], v[144:147], v[160:163], v[60:63]
	v_mfma_f32_16x16x32_bf16 v[56:59], v[152:155], v[160:163], v[56:59]
	v_mfma_f32_16x16x32_bf16 v[52:55], v[144:147], v[178:181], v[52:55]
	v_mfma_f32_16x16x32_bf16 v[48:51], v[152:155], v[178:181], v[48:51]
	v_mfma_f32_16x16x32_bf16 v[44:47], v[144:147], v[186:189], v[44:47]
	v_mfma_f32_16x16x32_bf16 v[40:43], v[152:155], v[186:189], v[40:43]
	v_mfma_f32_16x16x32_bf16 v[36:39], v[144:147], v[208:211], v[36:39]
	v_mfma_f32_16x16x32_bf16 v[32:35], v[152:155], v[208:211], v[32:35]
	v_mfma_f32_16x16x32_bf16 v[60:63], v[148:151], v[164:167], v[60:63]
	v_mfma_f32_16x16x32_bf16 v[56:59], v[156:159], v[164:167], v[56:59]
	v_mfma_f32_16x16x32_bf16 v[52:55], v[148:151], v[182:185], v[52:55]
	v_mfma_f32_16x16x32_bf16 v[48:51], v[156:159], v[182:185], v[48:51]
	v_mfma_f32_16x16x32_bf16 v[44:47], v[148:151], v[204:207], v[44:47]
	v_mfma_f32_16x16x32_bf16 v[40:43], v[156:159], v[204:207], v[40:43]
	v_mfma_f32_16x16x32_bf16 v[36:39], v[148:151], v[216:219], v[36:39]
	v_mfma_f32_16x16x32_bf16 v[32:35], v[156:159], v[216:219], v[32:35]
	s_setprio 0
	s_barrier
	s_add_i32 s26, s62, s37
	s_mov_b32 m0, s26
	ds_read_b128 v[160:163], v215 offset:49152
	ds_read_b128 v[164:167], v215 offset:50176
	ds_read_b128 v[178:181], v215 offset:51200
	ds_read_b128 v[182:185], v215 offset:52224
	ds_read_b128 v[186:189], v215 offset:53248
	ds_read_b128 v[204:207], v215 offset:54272
	ds_read_b128 v[208:211], v215 offset:55296
	ds_read_b128 v[216:219], v215 offset:56320
	global_load_lds_dwordx4 v192, s[72:73]
	s_add_i32 m0, s26, 0x2000
	s_add_u32 s24, s24, 0x100080
	s_addc_u32 s25, s25, 0
	s_add_i32 s26, s63, s37
	global_load_lds_dwordx4 v172, s[72:73]
	s_mov_b32 m0, s26
	s_nop 0
	global_load_lds_dwordx4 v192, s[24:25]
	s_add_i32 m0, s26, 0x2000
	s_nop 0
	global_load_lds_dwordx4 v172, s[24:25]
	s_mov_b32 m0, s50
	s_nop 0
	global_load_lds_dwordx4 v168, s[98:99]
	s_mov_b32 m0, s51
	s_nop 0
	global_load_lds_dwordx4 v170, s[98:99]
	s_waitcnt vmcnt(8)
	s_waitcnt lgkmcnt(0)
	s_barrier
	s_setprio 1
	v_mfma_f32_16x16x32_bf16 v[92:95], v[128:131], v[160:163], v[92:95]
	v_mfma_f32_16x16x32_bf16 v[88:91], v[136:139], v[160:163], v[88:91]
	v_mfma_f32_16x16x32_bf16 v[84:87], v[128:131], v[178:181], v[84:87]
	v_mfma_f32_16x16x32_bf16 v[80:83], v[136:139], v[178:181], v[80:83]
	v_mfma_f32_16x16x32_bf16 v[76:79], v[128:131], v[186:189], v[76:79]
	v_mfma_f32_16x16x32_bf16 v[72:75], v[136:139], v[186:189], v[72:75]
	v_mfma_f32_16x16x32_bf16 v[68:71], v[128:131], v[208:211], v[68:71]
	v_mfma_f32_16x16x32_bf16 v[64:67], v[136:139], v[208:211], v[64:67]
	v_mfma_f32_16x16x32_bf16 v[92:95], v[132:135], v[164:167], v[92:95]
	v_mfma_f32_16x16x32_bf16 v[88:91], v[140:143], v[164:167], v[88:91]
	v_mfma_f32_16x16x32_bf16 v[84:87], v[132:135], v[182:185], v[84:87]
	v_mfma_f32_16x16x32_bf16 v[80:83], v[140:143], v[182:185], v[80:83]
	v_mfma_f32_16x16x32_bf16 v[76:79], v[132:135], v[204:207], v[76:79]
	v_mfma_f32_16x16x32_bf16 v[72:75], v[140:143], v[204:207], v[72:75]
	v_mfma_f32_16x16x32_bf16 v[68:71], v[132:135], v[216:219], v[68:71]
	v_mfma_f32_16x16x32_bf16 v[64:67], v[140:143], v[216:219], v[64:67]
	s_setprio 0
	s_setprio 1
	v_mfma_f32_16x16x32_bf16 v[28:31], v[144:147], v[160:163], v[28:31]
	v_mfma_f32_16x16x32_bf16 v[24:27], v[152:155], v[160:163], v[24:27]
	v_mfma_f32_16x16x32_bf16 v[20:23], v[144:147], v[178:181], v[20:23]
	v_mfma_f32_16x16x32_bf16 v[16:19], v[152:155], v[178:181], v[16:19]
	v_mfma_f32_16x16x32_bf16 v[12:15], v[144:147], v[186:189], v[12:15]
	v_mfma_f32_16x16x32_bf16 v[8:11], v[152:155], v[186:189], v[8:11]
	v_mfma_f32_16x16x32_bf16 v[4:7], v[144:147], v[208:211], v[4:7]
	v_mfma_f32_16x16x32_bf16 v[0:3], v[152:155], v[208:211], v[0:3]
	v_mfma_f32_16x16x32_bf16 v[28:31], v[148:151], v[164:167], v[28:31]
	v_mfma_f32_16x16x32_bf16 v[24:27], v[156:159], v[164:167], v[24:27]
	v_mfma_f32_16x16x32_bf16 v[20:23], v[148:151], v[182:185], v[20:23]
	v_mfma_f32_16x16x32_bf16 v[16:19], v[156:159], v[182:185], v[16:19]
	v_mfma_f32_16x16x32_bf16 v[12:15], v[148:151], v[204:207], v[12:15]
	v_mfma_f32_16x16x32_bf16 v[8:11], v[156:159], v[204:207], v[8:11]
	v_mfma_f32_16x16x32_bf16 v[4:7], v[148:151], v[216:219], v[4:7]
	v_mfma_f32_16x16x32_bf16 v[0:3], v[156:159], v[216:219], v[0:3]
	s_setprio 0
	s_barrier
	s_add_i32 s59, s59, 2
	s_add_u32 s4, s4, 0x100
	s_addc_u32 s5, s5, 0
	s_add_u32 s33, s33, 0x100
	s_addc_u32 s58, s58, 0
	s_cmp_gt_u32 s59, 61
	s_cbranch_scc0 .LBB0_1335
	s_and_b64 vcc, exec, s[14:15]
	s_cbranch_vccz .LBB0_1338
	s_barrier
